# write-through also for the P0 normalised rows and the scan chunk outputs
# speedup vs baseline: 1.0180x; 1.0108x over previous
; __device__ __forceinline__ void p0_prep(const Params& p, LAS unsigned char* lds) {
;     ...
;         for (int row = blockIdx.x * 8 + wave; row < MALL; row += 4 * stride) {
;             f32x4 v[4][4]; float sq[4];
; #pragma unroll
;             for (int u = 0; u < 4; ++u) {
;                 const int r = row + u * stride, rc = r < MALL ? r : row;
;                 const float* xr = (rc < MP) ? p.in[0] + (size_t)rc * D : p.in[1] + (size_t)(rc - MP) * D;
;                 sq[u] = 0.f;
; #pragma unroll
;                 for (int j = 0; j < 4; ++j) v[u][j] = *(const f32x4*)(xr + lane * 4 + 256 * j);
;             }
; #pragma unroll
;             for (int u = 0; u < 4; ++u) {
; #pragma unroll
;                 for (int j = 0; j < 4; ++j) sq[u] += v[u][j][0] * v[u][j][0] + v[u][j][1] * v[u][j][1] + v[u][j][2] * v[u][j][2] + v[u][j][3] * v[u][j][3];
;                 const float rstd = rsqrtf(wave_sum(sq[u]) * (1.f / D) + EPS);
.LBB0_56:
	v_add_u32_e32 v18, 0xffffc000, v84
	v_ashrrev_i32_e32 v85, 31, v84
	v_cmp_gt_i32_e32 vcc, s35, v84
	v_add_u32_e32 v86, s30, v84
	v_cmp_gt_i32_e64 s[8:9], s3, v86
	v_cndmask_b32_e32 v19, 0, v85, vcc
	v_cndmask_b32_e32 v18, v18, v84, vcc
	v_cndmask_b32_e32 v21, v93, v94, vcc
	v_cndmask_b32_e32 v20, v95, v96, vcc
	v_lshlrev_b64 v[18:19], 12, v[18:19]
	v_lshl_add_u64 v[18:19], v[20:21], 0, v[18:19]
	v_lshl_add_u64 v[18:19], v[18:19], 0, v[134:135]
	global_load_dwordx4 v[46:49], v[18:19], off
	global_load_dwordx4 v[42:45], v[18:19], off offset:1024
	global_load_dwordx4 v[38:41], v[18:19], off offset:2048
	s_waitcnt lgkmcnt(0)
	global_load_dwordx4 v[34:37], v[18:19], off offset:3072
	v_cndmask_b32_e64 v18, v84, v86, s[8:9]
	v_ashrrev_i32_e32 v19, 31, v18
	v_add_u32_e32 v20, 0xffffc000, v18
	v_cmp_gt_i32_e32 vcc, s35, v18
	s_waitcnt vmcnt(3)
	v_mov_b32_e32 v26, v49
	v_cndmask_b32_e32 v19, 0, v19, vcc
	v_cndmask_b32_e32 v18, v20, v18, vcc
	v_cndmask_b32_e32 v21, v93, v94, vcc
	v_cndmask_b32_e32 v20, v95, v96, vcc
	v_lshlrev_b64 v[18:19], 12, v[18:19]
	v_lshl_add_u64 v[18:19], v[20:21], 0, v[18:19]
	v_lshl_add_u64 v[18:19], v[18:19], 0, v[134:135]
	global_load_dwordx4 v[78:81], v[18:19], off
	global_load_dwordx4 v[74:77], v[18:19], off offset:1024
	global_load_dwordx4 v[70:73], v[18:19], off offset:2048
	global_load_dwordx4 v[66:69], v[18:19], off offset:3072
	v_add_u32_e32 v18, s30, v86
	v_cmp_gt_i32_e64 s[6:7], s3, v18
	v_add_u32_e32 v98, s30, v18
	v_cmp_gt_i32_e32 vcc, s3, v98
	v_cndmask_b32_e64 v20, v84, v18, s[6:7]
	v_ashrrev_i32_e32 v18, 31, v20
	v_add_u32_e32 v21, 0xffffc000, v20
	v_cmp_gt_i32_e64 s[0:1], s35, v20
	v_cndmask_b32_e32 v22, v84, v98, vcc
	v_ashrrev_i32_e32 v23, 31, v22
	v_cndmask_b32_e64 v19, 0, v18, s[0:1]
	v_cndmask_b32_e64 v18, v21, v20, s[0:1]
	v_add_u32_e32 v24, 0xffffc000, v22
	v_cndmask_b32_e64 v21, v93, v94, s[0:1]
	v_cndmask_b32_e64 v20, v95, v96, s[0:1]
	v_cmp_gt_i32_e64 s[0:1], s35, v22
	v_lshlrev_b64 v[18:19], 12, v[18:19]
	v_lshl_add_u64 v[18:19], v[20:21], 0, v[18:19]
	v_cndmask_b32_e64 v23, 0, v23, s[0:1]
	v_cndmask_b32_e64 v22, v24, v22, s[0:1]
	v_lshlrev_b64 v[20:21], 12, v[22:23]
	v_lshl_add_u64 v[18:19], v[18:19], 0, v[134:135]
	v_mov_b32_e32 v22, v47
	s_waitcnt vmcnt(6)
	v_mov_b32_e32 v23, v43
	v_cndmask_b32_e64 v25, v93, v94, s[0:1]
	v_cndmask_b32_e64 v24, v95, v96, s[0:1]
	global_load_dwordx4 v[62:65], v[18:19], off
	global_load_dwordx4 v[58:61], v[18:19], off offset:1024
	global_load_dwordx4 v[54:57], v[18:19], off offset:2048
	global_load_dwordx4 v[50:53], v[18:19], off offset:3072
	v_mov_b32_e32 v18, v46
	v_mov_b32_e32 v19, v42
	s_waitcnt vmcnt(9)
	v_mov_b32_e32 v30, v39
	s_waitcnt vmcnt(8)
	v_mov_b32_e32 v31, v35
	v_pk_mul_f32 v[22:23], v[22:23], v[22:23]
	v_lshl_add_u64 v[20:21], v[24:25], 0, v[20:21]
	v_mov_b32_e32 v24, v48
	v_mov_b32_e32 v25, v44
	v_mov_b32_e32 v28, v38
	v_mov_b32_e32 v29, v34
	v_pk_mul_f32 v[30:31], v[30:31], v[30:31]
	v_pk_fma_f32 v[18:19], v[18:19], v[18:19], v[22:23]
	v_mov_b32_e32 v27, v45
	v_mov_b32_e32 v32, v40
	v_mov_b32_e32 v33, v36
	v_pk_fma_f32 v[22:23], v[28:29], v[28:29], v[30:31]
	v_pk_fma_f32 v[18:19], v[24:25], v[24:25], v[18:19]
	v_mov_b32_e32 v100, v41
	v_mov_b32_e32 v101, v37
	v_pk_fma_f32 v[22:23], v[32:33], v[32:33], v[22:23]
	v_pk_fma_f32 v[18:19], v[26:27], v[26:27], v[18:19]
	v_pk_fma_f32 v[22:23], v[100:101], v[100:101], v[22:23]
	v_add_f32_e32 v18, v18, v19
	v_lshl_add_u64 v[20:21], v[20:21], 0, v[134:135]
	v_add_f32_e32 v18, v18, v22
	v_add_f32_e32 v87, v18, v23
	global_load_dwordx4 v[30:33], v[20:21], off
	global_load_dwordx4 v[26:29], v[20:21], off offset:1024
	global_load_dwordx4 v[22:25], v[20:21], off offset:2048
	s_nop 0
	global_load_dwordx4 v[18:21], v[20:21], off offset:3072
	ds_bpermute_b32 v99, v1, v87
	s_waitcnt lgkmcnt(0)
	v_add_f32_e32 v87, v87, v99
	ds_bpermute_b32 v99, v88, v87
	s_waitcnt lgkmcnt(0)
	v_add_f32_e32 v87, v87, v99
	ds_bpermute_b32 v99, v89, v87
	s_waitcnt lgkmcnt(0)
	v_add_f32_e32 v87, v87, v99
	ds_bpermute_b32 v99, v90, v87
	s_waitcnt vmcnt(11)
	v_mul_f32_e32 v100, v79, v79
	s_waitcnt lgkmcnt(0)
	v_add_f32_e32 v87, v87, v99
	ds_bpermute_b32 v99, v91, v87
	s_waitcnt vmcnt(10)
	v_mul_f32_e32 v101, v75, v75
	s_waitcnt vmcnt(9)
	v_mul_f32_e32 v102, v71, v71
	v_fmac_f32_e32 v100, v78, v78
	v_fmac_f32_e32 v101, v74, v74
	s_waitcnt lgkmcnt(0)
	v_add_f32_e32 v87, v87, v99
	ds_bpermute_b32 v99, v92, v87
	s_waitcnt vmcnt(8)
	v_mul_f32_e32 v103, v67, v67
	v_fmac_f32_e32 v102, v70, v70
	v_fmac_f32_e32 v100, v80, v80
	v_fmac_f32_e32 v101, v76, v76
	s_waitcnt lgkmcnt(0)
	v_add_f32_e32 v87, v87, v99
	v_fmac_f32_e32 v103, v66, v66
	v_fmac_f32_e32 v102, v72, v72
	v_fmac_f32_e32 v100, v81, v81
	v_fmac_f32_e32 v101, v77, v77
	v_fmamk_f32 v87, v87, 0x3a800000, v97
	v_fmac_f32_e32 v103, v68, v68
	v_fmac_f32_e32 v102, v73, v73
	v_add_f32_e32 v100, v100, v101
	v_mul_f32_e32 v99, 0x4b800000, v87
	v_cmp_gt_f32_e64 s[0:1], s38, v87
	v_fmac_f32_e32 v103, v69, v69
	s_nop 0
	v_cndmask_b32_e64 v87, v87, v99, s[0:1]
	v_add_f32_e32 v99, v100, v102
	v_add_f32_e32 v99, v99, v103
	v_rsq_f32_e32 v87, v87
	ds_bpermute_b32 v101, v1, v99
	v_mul_f32_e32 v100, 0x45800000, v87
	v_cndmask_b32_e64 v100, v87, v100, s[0:1]
	s_waitcnt lgkmcnt(0)
	v_add_f32_e32 v87, v99, v101
	ds_bpermute_b32 v99, v88, v87
	v_pk_mul_f32 v[42:43], v[42:43], v[100:101] op_sel_hi:[1,0]
	v_pk_mul_f32 v[44:45], v[44:45], v[100:101] op_sel_hi:[1,0]
	v_pk_mul_f32 v[42:43], v[6:7], v[42:43]
	v_pk_mul_f32 v[44:45], v[8:9], v[44:45]
	s_waitcnt lgkmcnt(0)
; __device__ __forceinline__ void p0_prep(const Params& p, LAS unsigned char* lds) {
;     ...
;             for (int u = 0; u < 4; ++u) {
; #pragma unroll
;                 for (int j = 0; j < 4; ++j) sq[u] += v[u][j][0] * v[u][j][0] + v[u][j][1] * v[u][j][1] + v[u][j][2] * v[u][j][2] + v[u][j][3] * v[u][j][3];
;                 const float rstd = rsqrtf(wave_sum(sq[u]) * (1.f / D) + EPS);
;                 const int r = row + u * stride;
;                 if (r < MALL) {
;                     h16* o = (h16*)(ws + OFF_XN16) + (size_t)r * D;
; #pragma unroll
;                     for (int j = 0; j < 4; ++j) *(h16x4*)(o + lane * 4 + 256 * j) = pack4(v[u][j] * rstd * w4[j]);
;                 }
;             }
	v_add_f32_e32 v87, v87, v99
	ds_bpermute_b32 v99, v89, v87
	v_cvt_pk_f16_f32 v45, v44, v45
	v_cvt_pk_f16_f32 v44, v42, v43
	v_pk_mul_f32 v[34:35], v[34:35], v[100:101] op_sel_hi:[1,0]
	v_pk_mul_f32 v[36:37], v[36:37], v[100:101] op_sel_hi:[1,0]
	s_waitcnt lgkmcnt(0)
	v_add_f32_e32 v42, v87, v99
	ds_bpermute_b32 v43, v90, v42
	v_pk_mul_f32 v[38:39], v[38:39], v[100:101] op_sel_hi:[1,0]
	v_pk_mul_f32 v[40:41], v[40:41], v[100:101] op_sel_hi:[1,0]
	v_pk_mul_f32 v[36:37], v[16:17], v[36:37]
	v_pk_mul_f32 v[34:35], v[14:15], v[34:35]
	s_waitcnt lgkmcnt(0)
	v_add_f32_e32 v42, v42, v43
	ds_bpermute_b32 v43, v91, v42
	v_pk_mul_f32 v[40:41], v[12:13], v[40:41]
	v_pk_mul_f32 v[38:39], v[10:11], v[38:39]
	v_cvt_pk_f16_f32 v37, v36, v37
	v_cvt_pk_f16_f32 v36, v34, v35
	v_lshlrev_b64 v[34:35], 11, v[84:85]
	v_cvt_pk_f16_f32 v41, v40, v41
	v_cvt_pk_f16_f32 v40, v38, v39
	v_lshl_add_u64 v[38:39], v[82:83], 0, v[34:35]
	s_waitcnt lgkmcnt(0)
	v_add_f32_e32 v34, v42, v43
	ds_bpermute_b32 v35, v92, v34
	v_pk_mul_f32 v[46:47], v[46:47], v[100:101] op_sel_hi:[1,0]
	v_pk_mul_f32 v[48:49], v[48:49], v[100:101] op_sel_hi:[1,0]
	v_pk_mul_f32 v[46:47], v[2:3], v[46:47]
	v_pk_mul_f32 v[48:49], v[4:5], v[48:49]
	s_nop 0
	v_cvt_pk_f16_f32 v49, v48, v49
	v_cvt_pk_f16_f32 v48, v46, v47
	global_store_dwordx2 v[38:39], v[48:49], off sc0 sc1
	global_store_dwordx2 v[38:39], v[44:45], off offset:512 sc0 sc1
	global_store_dwordx2 v[38:39], v[40:41], off offset:1024 sc0 sc1
	global_store_dwordx2 v[38:39], v[36:37], off offset:1536 sc0 sc1
	s_and_saveexec_b64 s[28:29], s[8:9]
	s_cbranch_execz .LBB0_58
	s_waitcnt lgkmcnt(0)
	v_add_f32_e32 v34, v34, v35
	v_fmamk_f32 v34, v34, 0x3a800000, v97
	v_mul_f32_e32 v35, 0x4b800000, v34
	v_cmp_gt_f32_e64 s[0:1], s38, v34
	v_ashrrev_i32_e32 v87, 31, v86
	s_nop 0
	v_cndmask_b32_e64 v34, v34, v35, s[0:1]
	v_rsq_f32_e32 v36, v34
	v_lshlrev_b64 v[34:35], 11, v[86:87]
	v_lshl_add_u64 v[34:35], v[82:83], 0, v[34:35]
	v_mul_f32_e32 v37, 0x45800000, v36
	v_cndmask_b32_e64 v36, v36, v37, s[0:1]
	v_pk_mul_f32 v[38:39], v[78:79], v[36:37] op_sel_hi:[1,0]
	v_pk_mul_f32 v[40:41], v[80:81], v[36:37] op_sel_hi:[1,0]
	v_pk_mul_f32 v[38:39], v[2:3], v[38:39]
	v_pk_mul_f32 v[40:41], v[4:5], v[40:41]
	s_nop 0
	v_cvt_pk_f16_f32 v41, v40, v41
	v_cvt_pk_f16_f32 v40, v38, v39
	global_store_dwordx2 v[34:35], v[40:41], off sc0 sc1
	v_pk_mul_f32 v[38:39], v[74:75], v[36:37] op_sel_hi:[1,0]
	v_pk_mul_f32 v[40:41], v[76:77], v[36:37] op_sel_hi:[1,0]
	v_pk_mul_f32 v[38:39], v[6:7], v[38:39]
	v_pk_mul_f32 v[40:41], v[8:9], v[40:41]
	s_nop 0
	v_cvt_pk_f16_f32 v41, v40, v41
	v_cvt_pk_f16_f32 v40, v38, v39
	global_store_dwordx2 v[34:35], v[40:41], off offset:512 sc0 sc1
	v_pk_mul_f32 v[38:39], v[70:71], v[36:37] op_sel_hi:[1,0]
	v_pk_mul_f32 v[40:41], v[72:73], v[36:37] op_sel_hi:[1,0]
	v_pk_mul_f32 v[38:39], v[10:11], v[38:39]
	v_pk_mul_f32 v[40:41], v[12:13], v[40:41]
	s_nop 0
	v_cvt_pk_f16_f32 v41, v40, v41
	v_cvt_pk_f16_f32 v40, v38, v39
	v_pk_mul_f32 v[38:39], v[66:67], v[36:37] op_sel_hi:[1,0]
	v_pk_mul_f32 v[36:37], v[68:69], v[36:37] op_sel_hi:[1,0]
	v_pk_mul_f32 v[38:39], v[14:15], v[38:39]
	v_pk_mul_f32 v[36:37], v[16:17], v[36:37]
	global_store_dwordx2 v[34:35], v[40:41], off offset:1024 sc0 sc1
	v_cvt_pk_f16_f32 v37, v36, v37
	v_cvt_pk_f16_f32 v36, v38, v39
	global_store_dwordx2 v[34:35], v[36:37], off offset:1536 sc0 sc1
; __device__ __forceinline__ void p0_prep(const Params& p, LAS unsigned char* lds) {
;     ...
;             for (int u = 0; u < 4; ++u) {
; #pragma unroll
;                 for (int j = 0; j < 4; ++j) sq[u] += v[u][j][0] * v[u][j][0] + v[u][j][1] * v[u][j][1] + v[u][j][2] * v[u][j][2] + v[u][j][3] * v[u][j][3];
;                 const float rstd = rsqrtf(wave_sum(sq[u]) * (1.f / D) + EPS);
;                 const int r = row + u * stride;
;                 if (r < MALL) {
;                     h16* o = (h16*)(ws + OFF_XN16) + (size_t)r * D;
; #pragma unroll
;                     for (int j = 0; j < 4; ++j) *(h16x4*)(o + lane * 4 + 256 * j) = pack4(v[u][j] * rstd * w4[j]);
;                 }
;             }
.LBB0_58:
	s_or_b64 exec, exec, s[28:29]
	s_waitcnt vmcnt(11)
	v_mul_f32_e32 v34, v63, v63
	s_waitcnt vmcnt(10) lgkmcnt(0)
	v_mul_f32_e32 v35, v59, v59
	v_fmac_f32_e32 v34, v62, v62
	v_fmac_f32_e32 v35, v58, v58
	v_fmac_f32_e32 v34, v64, v64
	v_fmac_f32_e32 v35, v60, v60
	v_fmac_f32_e32 v34, v65, v65
	v_fmac_f32_e32 v35, v61, v61
	v_add_f32_e32 v34, v34, v35
	s_waitcnt vmcnt(9)
	v_mul_f32_e32 v35, v55, v55
	v_fmac_f32_e32 v35, v54, v54
	v_fmac_f32_e32 v35, v56, v56
	v_fmac_f32_e32 v35, v57, v57
	v_add_f32_e32 v34, v34, v35
	s_waitcnt vmcnt(8)
	v_mul_f32_e32 v35, v51, v51
	v_fmac_f32_e32 v35, v50, v50
	v_fmac_f32_e32 v35, v52, v52
	v_fmac_f32_e32 v35, v53, v53
	v_add_f32_e32 v34, v34, v35
	ds_bpermute_b32 v35, v1, v34
	s_waitcnt lgkmcnt(0)
	v_add_f32_e32 v34, v34, v35
	ds_bpermute_b32 v35, v88, v34
	s_waitcnt lgkmcnt(0)
	v_add_f32_e32 v34, v34, v35
	ds_bpermute_b32 v35, v89, v34
	s_waitcnt lgkmcnt(0)
	v_add_f32_e32 v34, v34, v35
	ds_bpermute_b32 v35, v90, v34
	s_waitcnt lgkmcnt(0)
	v_add_f32_e32 v34, v34, v35
	ds_bpermute_b32 v35, v91, v34
	s_waitcnt lgkmcnt(0)
	v_add_f32_e32 v34, v34, v35
	ds_bpermute_b32 v35, v92, v34
	s_and_saveexec_b64 s[8:9], s[6:7]
	s_cbranch_execz .LBB0_60
	s_waitcnt lgkmcnt(0)
	v_add_f32_e32 v34, v34, v35
	v_fmamk_f32 v34, v34, 0x3a800000, v97
	v_mul_f32_e32 v35, 0x4b800000, v34
	v_cmp_gt_f32_e64 s[0:1], s38, v34
	s_nop 1
	v_cndmask_b32_e64 v34, v34, v35, s[0:1]
	v_rsq_f32_e32 v36, v34
	v_add_u32_e32 v34, s31, v84
	v_ashrrev_i32_e32 v35, 31, v34
	v_lshlrev_b64 v[34:35], 11, v[34:35]
	v_mul_f32_e32 v37, 0x45800000, v36
	v_cndmask_b32_e64 v36, v36, v37, s[0:1]
	v_pk_mul_f32 v[38:39], v[62:63], v[36:37] op_sel_hi:[1,0]
	v_pk_mul_f32 v[40:41], v[64:65], v[36:37] op_sel_hi:[1,0]
	v_pk_mul_f32 v[38:39], v[2:3], v[38:39]
	v_pk_mul_f32 v[40:41], v[4:5], v[40:41]
	v_lshl_add_u64 v[34:35], v[82:83], 0, v[34:35]
	v_cvt_pk_f16_f32 v41, v40, v41
	v_cvt_pk_f16_f32 v40, v38, v39
	global_store_dwordx2 v[34:35], v[40:41], off sc0 sc1
	v_pk_mul_f32 v[38:39], v[58:59], v[36:37] op_sel_hi:[1,0]
	v_pk_mul_f32 v[40:41], v[60:61], v[36:37] op_sel_hi:[1,0]
	v_pk_mul_f32 v[38:39], v[6:7], v[38:39]
	v_pk_mul_f32 v[40:41], v[8:9], v[40:41]
	s_nop 0
	v_cvt_pk_f16_f32 v41, v40, v41
	v_cvt_pk_f16_f32 v40, v38, v39
	global_store_dwordx2 v[34:35], v[40:41], off offset:512 sc0 sc1
	v_pk_mul_f32 v[38:39], v[54:55], v[36:37] op_sel_hi:[1,0]
	v_pk_mul_f32 v[40:41], v[56:57], v[36:37] op_sel_hi:[1,0]
	v_pk_mul_f32 v[38:39], v[10:11], v[38:39]
	v_pk_mul_f32 v[40:41], v[12:13], v[40:41]
	s_nop 0
	v_cvt_pk_f16_f32 v41, v40, v41
	v_cvt_pk_f16_f32 v40, v38, v39
	v_pk_mul_f32 v[38:39], v[50:51], v[36:37] op_sel_hi:[1,0]
	v_pk_mul_f32 v[36:37], v[52:53], v[36:37] op_sel_hi:[1,0]
	v_pk_mul_f32 v[38:39], v[14:15], v[38:39]
	v_pk_mul_f32 v[36:37], v[16:17], v[36:37]
	global_store_dwordx2 v[34:35], v[40:41], off offset:1024 sc0 sc1
	v_cvt_pk_f16_f32 v37, v36, v37
	v_cvt_pk_f16_f32 v36, v38, v39
	global_store_dwordx2 v[34:35], v[36:37], off offset:1536 sc0 sc1
.LBB0_60:
	s_or_b64 exec, exec, s[8:9]
	s_waitcnt vmcnt(7)
	v_mul_f32_e32 v34, v31, v31
	s_waitcnt vmcnt(6) lgkmcnt(0)
	v_mul_f32_e32 v35, v27, v27
	v_fmac_f32_e32 v34, v30, v30
	v_fmac_f32_e32 v35, v26, v26
	v_fmac_f32_e32 v34, v32, v32
	v_fmac_f32_e32 v35, v28, v28
	v_fmac_f32_e32 v34, v33, v33
	v_fmac_f32_e32 v35, v29, v29
	v_add_f32_e32 v34, v34, v35
	s_waitcnt vmcnt(5)
	v_mul_f32_e32 v35, v23, v23
	v_fmac_f32_e32 v35, v22, v22
	v_fmac_f32_e32 v35, v24, v24
	v_fmac_f32_e32 v35, v25, v25
	v_add_f32_e32 v34, v34, v35
	s_waitcnt vmcnt(4)
	v_mul_f32_e32 v35, v19, v19
	v_fmac_f32_e32 v35, v18, v18
	v_fmac_f32_e32 v35, v20, v20
	v_fmac_f32_e32 v35, v21, v21
	v_add_f32_e32 v34, v34, v35
	ds_bpermute_b32 v35, v1, v34
	s_waitcnt lgkmcnt(0)
	v_add_f32_e32 v34, v34, v35
	ds_bpermute_b32 v35, v88, v34
	s_waitcnt lgkmcnt(0)
	v_add_f32_e32 v34, v34, v35
	ds_bpermute_b32 v35, v89, v34
	s_waitcnt lgkmcnt(0)
	v_add_f32_e32 v34, v34, v35
	ds_bpermute_b32 v35, v90, v34
	s_waitcnt lgkmcnt(0)
	v_add_f32_e32 v34, v34, v35
	ds_bpermute_b32 v35, v91, v34
	s_waitcnt lgkmcnt(0)
	v_add_f32_e32 v34, v34, v35
	ds_bpermute_b32 v35, v92, v34
	s_and_saveexec_b64 s[0:1], vcc
	s_cbranch_execz .LBB0_55
	s_waitcnt lgkmcnt(0)
	v_add_f32_e32 v34, v34, v35
	v_fmamk_f32 v34, v34, 0x3a800000, v97
	v_mul_f32_e32 v35, 0x4b800000, v34
	v_cmp_gt_f32_e32 vcc, s38, v34
	s_nop 1
	v_cndmask_b32_e32 v34, v34, v35, vcc
	v_rsq_f32_e32 v36, v34
	v_add_u32_e32 v34, s34, v84
	v_ashrrev_i32_e32 v35, 31, v34
	v_lshlrev_b64 v[34:35], 11, v[34:35]
	v_mul_f32_e32 v37, 0x45800000, v36
	v_cndmask_b32_e32 v36, v36, v37, vcc
	v_pk_mul_f32 v[30:31], v[30:31], v[36:37] op_sel_hi:[1,0]
	v_pk_mul_f32 v[32:33], v[32:33], v[36:37] op_sel_hi:[1,0]
	v_pk_mul_f32 v[26:27], v[26:27], v[36:37] op_sel_hi:[1,0]
	v_pk_mul_f32 v[28:29], v[28:29], v[36:37] op_sel_hi:[1,0]
	v_pk_mul_f32 v[22:23], v[22:23], v[36:37] op_sel_hi:[1,0]
	v_pk_mul_f32 v[24:25], v[24:25], v[36:37] op_sel_hi:[1,0]
	v_pk_mul_f32 v[18:19], v[18:19], v[36:37] op_sel_hi:[1,0]
	v_pk_mul_f32 v[20:21], v[20:21], v[36:37] op_sel_hi:[1,0]
	v_pk_mul_f32 v[32:33], v[4:5], v[32:33]
	v_pk_mul_f32 v[30:31], v[2:3], v[30:31]
	v_pk_mul_f32 v[28:29], v[8:9], v[28:29]
	v_pk_mul_f32 v[26:27], v[6:7], v[26:27]
	v_pk_mul_f32 v[24:25], v[12:13], v[24:25]
	v_pk_mul_f32 v[22:23], v[10:11], v[22:23]
	v_pk_mul_f32 v[20:21], v[16:17], v[20:21]
	v_pk_mul_f32 v[18:19], v[14:15], v[18:19]
	v_lshl_add_u64 v[34:35], v[82:83], 0, v[34:35]
	v_cvt_pk_f16_f32 v33, v32, v33
	v_cvt_pk_f16_f32 v32, v30, v31
	v_cvt_pk_f16_f32 v29, v28, v29
	v_cvt_pk_f16_f32 v28, v26, v27
	v_cvt_pk_f16_f32 v25, v24, v25
	v_cvt_pk_f16_f32 v24, v22, v23
	v_cvt_pk_f16_f32 v21, v20, v21
	v_cvt_pk_f16_f32 v20, v18, v19
	global_store_dwordx2 v[34:35], v[32:33], off sc0 sc1
	global_store_dwordx2 v[34:35], v[28:29], off offset:512 sc0 sc1
	global_store_dwordx2 v[34:35], v[24:25], off offset:1024 sc0 sc1
	global_store_dwordx2 v[34:35], v[20:21], off offset:1536 sc0 sc1
	s_branch .LBB0_55

; #define LAS __attribute__((address_space(3)))
; __device__ __forceinline__ void rwkv_scan_prompt(const Params& p, LAS unsigned char* lds, int bh, int rq) {
;     ...
;             const LAS float* ob = OPS + buf * TC * 6 * 64;
;             f32x4 r4 = *(const LAS f32x4*)(ob + cg_ * 4), d4 = *(const LAS f32x4*)(ob + 64 + cg_ * 4), k4 = *(const LAS f32x4*)(ob + 128 + cg_ * 4),
;                   a4 = *(const LAS f32x4*)(ob + 256 + cg_ * 4), b4 = *(const LAS f32x4*)(ob + 320 + cg_ * 4);
;             float vv = ob[192 + rq * 16 + rloc];
;             f32x4 rp = r4;
; #pragma unroll
;             for (int tk = 0; tk < TC; ++tk) {
;                 f32x4 nr4 = r4, nd4 = d4, nk4 = k4, na4 = a4, nb4 = b4; float nvv = vv;
;                 if (tk < TC - 1) {
;                     const LAS float* o = ob + (tk + 1) * 6 * 64;
;                     nr4 = *(const LAS f32x4*)(o + cg_ * 4); nd4 = *(const LAS f32x4*)(o + 64 + cg_ * 4); nk4 = *(const LAS f32x4*)(o + 128 + cg_ * 4);
;                     na4 = *(const LAS f32x4*)(o + 256 + cg_ * 4); nb4 = *(const LAS f32x4*)(o + 320 + cg_ * 4);
;                     nvv = o[192 + rq * 16 + rloc];
;                 }
;                 __builtin_amdgcn_sched_barrier(0);
;                 typedef float f32x2_ __attribute__((ext_vector_type(2)));
;                 f32x2_ ta = (f32x2_){S[0], S[1]} * (f32x2_){a4[0], a4[1]}; ta = (f32x2_){S[2], S[3]} * (f32x2_){a4[2], a4[3]} + ta;
;                 f32x2_ ty = (f32x2_){S[0], S[1]} * (f32x2_){rp[0], rp[1]}; ty = (f32x2_){S[2], S[3]} * (f32x2_){rp[2], rp[3]} + ty;
;                 const f32x4 T = S * d4 + vv * k4;
;                 float sa = ta[0] + ta[1];
;                 float yp = ty[0] + ty[1];
;                 sa = dpp_add<0xB1>(sa); yp = dpp_add<0xB1>(yp);
;                 sa = dpp_add<0x4E>(sa); yp = dpp_add<0x4E>(yp);
;                 sa = dpp_add<0x124>(sa); yp = dpp_add<0x124>(yp);
;                 sa = dpp_add<0x128>(sa); yp = dpp_add<0x128>(yp);
;                 if (tk > 0) yk[(tk - 1) >> 4] = (cg_ == ((tk - 1) & 15)) ? yp : yk[(tk - 1) >> 4];
;                 S = sa * b4 + T;
;                 rp = r4;
;                 r4 = nr4; d4 = nd4; k4 = nk4; a4 = na4; b4 = nb4; vv = nvv;
;             }
.LBB0_336:
	s_and_b32 s95, s73, 1
	s_and_saveexec_b64 s[74:75], s[38:39]
	s_xor_b64 s[74:75], exec, s[74:75]
	s_cbranch_execz .LBB0_338
	s_mul_i32 s78, s95, 0xc000
	s_add_i32 s78, s78, 0
	v_lshl_add_u32 v28, v36, 2, s78
	v_lshl_add_u32 v29, v154, 2, s78
	ds_read_b128 v[30:33], v28
	ds_read_b128 v[160:163], v28 offset:256
	ds_read_b128 v[164:167], v28 offset:512
	ds_read_b128 v[168:171], v28 offset:1024
	ds_read2st64_b32 v[34:35], v29 offset0:3 offset1:9
	ds_read_b128 v[172:175], v28 offset:1280
	ds_read_b128 v[176:179], v28 offset:1536
	ds_read_b128 v[180:183], v28 offset:1792
	ds_read_b128 v[184:187], v28 offset:2048
	ds_read_b128 v[188:191], v28 offset:2560
	ds_read_b128 v[192:195], v28 offset:2816
	s_waitcnt lgkmcnt(7)
	v_pk_mul_f32 v[170:171], v[26:27], v[170:171]
	s_waitcnt lgkmcnt(6)
	v_pk_mul_f32 v[164:165], v[164:165], v[34:35] op_sel_hi:[1,0]
	v_pk_fma_f32 v[168:169], v[24:25], v[168:169], v[170:171]
	v_pk_mul_f32 v[166:167], v[166:167], v[34:35] op_sel_hi:[1,0]
	v_add_f32_e32 v168, v168, v169
	v_pk_fma_f32 v[26:27], v[26:27], v[162:163], v[166:167]
	v_pk_fma_f32 v[24:25], v[24:25], v[160:161], v[164:165]
	v_add_f32_dpp v168, v168, v168 quad_perm:[1,0,3,2] row_mask:0xf bank_mask:0xf bound_ctrl:1
	s_nop 1
	v_add_f32_dpp v168, v168, v168 quad_perm:[2,3,0,1] row_mask:0xf bank_mask:0xf bound_ctrl:1
	s_nop 1
	v_add_f32_dpp v168, v168, v168 row_ror:4 row_mask:0xf bank_mask:0xf bound_ctrl:1
	s_nop 1
	v_add_f32_dpp v168, v168, v168 row_ror:8 row_mask:0xf bank_mask:0xf bound_ctrl:1
	s_waitcnt lgkmcnt(5)
	v_pk_fma_f32 v[196:197], v[172:173], v[168:169], v[24:25] op_sel_hi:[1,0,1]
	v_pk_fma_f32 v[198:199], v[174:175], v[168:169], v[26:27] op_sel_hi:[1,0,1]
	ds_read_b128 v[24:27], v28 offset:3072
	ds_read_b128 v[160:163], v28 offset:3328
	ds_read_b128 v[164:167], v28 offset:3584
	ds_read_b128 v[168:171], v28 offset:4096
	ds_read_b128 v[172:175], v28 offset:4352
	ds_read_b32 v34, v29 offset:3840
	s_waitcnt lgkmcnt(7)
	v_pk_mul_f32 v[190:191], v[190:191], v[198:199]
	v_pk_mul_f32 v[32:33], v[32:33], v[198:199]
	v_pk_fma_f32 v[188:189], v[188:189], v[196:197], v[190:191]
	v_pk_fma_f32 v[30:31], v[30:31], v[196:197], v[32:33]
	v_pk_mul_f32 v[32:33], v[180:181], v[196:197]
	v_pk_mul_f32 v[180:181], v[182:183], v[198:199]
	v_mov_b32_e32 v182, v35
	v_add_f32_e32 v35, v188, v189
	v_add_f32_e32 v30, v30, v31
	v_pk_fma_f32 v[180:181], v[186:187], v[182:183], v[180:181] op_sel_hi:[1,0,1]
	v_add_f32_dpp v31, v35, v35 quad_perm:[1,0,3,2] row_mask:0xf bank_mask:0xf bound_ctrl:1
	v_add_f32_dpp v30, v30, v30 quad_perm:[1,0,3,2] row_mask:0xf bank_mask:0xf bound_ctrl:1
	v_pk_fma_f32 v[32:33], v[184:185], v[182:183], v[32:33] op_sel_hi:[1,0,1]
	v_add_f32_dpp v31, v31, v31 quad_perm:[2,3,0,1] row_mask:0xf bank_mask:0xf bound_ctrl:1
	v_add_f32_dpp v30, v30, v30 quad_perm:[2,3,0,1] row_mask:0xf bank_mask:0xf bound_ctrl:1
	s_nop 0
	v_add_f32_dpp v31, v31, v31 row_ror:4 row_mask:0xf bank_mask:0xf bound_ctrl:1
	v_add_f32_dpp v35, v30, v30 row_ror:4 row_mask:0xf bank_mask:0xf bound_ctrl:1
	s_nop 0
	v_add_f32_dpp v30, v31, v31 row_ror:8 row_mask:0xf bank_mask:0xf bound_ctrl:1
	v_add_f32_dpp v31, v35, v35 row_ror:8 row_mask:0xf bank_mask:0xf bound_ctrl:1
	v_cndmask_b32_e64 v201, 0, v31, s[6:7]
	s_waitcnt lgkmcnt(6)
	v_pk_fma_f32 v[196:197], v[192:193], v[30:31], v[32:33] op_sel_hi:[1,0,1]
	v_pk_fma_f32 v[198:199], v[194:195], v[30:31], v[180:181] op_sel_hi:[1,0,1]
	ds_read_b128 v[30:33], v28 offset:4608
	ds_read_b128 v[180:183], v28 offset:4864
	ds_read_b128 v[184:187], v28 offset:5120
	ds_read_b128 v[188:191], v28 offset:5632
	ds_read_b128 v[192:195], v28 offset:5888
	ds_read_b32 v200, v29 offset:5376
	s_waitcnt lgkmcnt(8)
	v_pk_mul_f32 v[170:171], v[170:171], v[198:199]
	v_pk_mul_f32 v[160:161], v[160:161], v[196:197]
	v_pk_fma_f32 v[168:169], v[168:169], v[196:197], v[170:171]
	v_pk_mul_f32 v[170:171], v[178:179], v[198:199]
	v_pk_mul_f32 v[162:163], v[162:163], v[198:199]
	v_pk_fma_f32 v[170:171], v[176:177], v[196:197], v[170:171]
	s_waitcnt lgkmcnt(6)
	v_pk_fma_f32 v[162:163], v[166:167], v[34:35], v[162:163] op_sel_hi:[1,0,1]
	v_pk_fma_f32 v[34:35], v[164:165], v[34:35], v[160:161] op_sel_hi:[1,0,1]
	v_add_f32_e32 v160, v168, v169
	v_add_f32_e32 v161, v170, v171
	s_nop 0
	v_add_f32_dpp v160, v160, v160 quad_perm:[1,0,3,2] row_mask:0xf bank_mask:0xf bound_ctrl:1
	v_add_f32_dpp v161, v161, v161 quad_perm:[1,0,3,2] row_mask:0xf bank_mask:0xf bound_ctrl:1
	s_nop 0
	v_add_f32_dpp v160, v160, v160 quad_perm:[2,3,0,1] row_mask:0xf bank_mask:0xf bound_ctrl:1
	v_add_f32_dpp v161, v161, v161 quad_perm:[2,3,0,1] row_mask:0xf bank_mask:0xf bound_ctrl:1
	s_nop 0
	v_add_f32_dpp v160, v160, v160 row_ror:4 row_mask:0xf bank_mask:0xf bound_ctrl:1
	v_add_f32_dpp v161, v161, v161 row_ror:4 row_mask:0xf bank_mask:0xf bound_ctrl:1
	s_nop 0
	v_add_f32_dpp v160, v160, v160 row_ror:8 row_mask:0xf bank_mask:0xf bound_ctrl:1
	v_add_f32_dpp v161, v161, v161 row_ror:8 row_mask:0xf bank_mask:0xf bound_ctrl:1
	v_cndmask_b32_e64 v199, v201, v161, s[8:9]
	v_pk_fma_f32 v[34:35], v[172:173], v[160:161], v[34:35] op_sel_hi:[1,0,1]
	v_pk_fma_f32 v[196:197], v[174:175], v[160:161], v[162:163] op_sel_hi:[1,0,1]
	ds_read_b128 v[160:163], v28 offset:6144
	ds_read_b128 v[164:167], v28 offset:6400
	ds_read_b128 v[168:171], v28 offset:6656
	ds_read_b128 v[172:175], v28 offset:7168
	ds_read_b128 v[176:179], v28 offset:7424
	ds_read_b32 v198, v29 offset:6912
	s_waitcnt lgkmcnt(8)
; #define LAS __attribute__((address_space(3)))
; __device__ __forceinline__ void rwkv_scan_prompt(const Params& p, LAS unsigned char* lds, int bh, int rq) {
;     ...
;             const LAS float* ob = OPS + buf * TC * 6 * 64;
;             f32x4 r4 = *(const LAS f32x4*)(ob + cg_ * 4), d4 = *(const LAS f32x4*)(ob + 64 + cg_ * 4), k4 = *(const LAS f32x4*)(ob + 128 + cg_ * 4),
;                   a4 = *(const LAS f32x4*)(ob + 256 + cg_ * 4), b4 = *(const LAS f32x4*)(ob + 320 + cg_ * 4);
;             float vv = ob[192 + rq * 16 + rloc];
;             f32x4 rp = r4;
; #pragma unroll
;             for (int tk = 0; tk < TC; ++tk) {
;                 f32x4 nr4 = r4, nd4 = d4, nk4 = k4, na4 = a4, nb4 = b4; float nvv = vv;
;                 if (tk < TC - 1) {
;                     const LAS float* o = ob + (tk + 1) * 6 * 64;
;                     nr4 = *(const LAS f32x4*)(o + cg_ * 4); nd4 = *(const LAS f32x4*)(o + 64 + cg_ * 4); nk4 = *(const LAS f32x4*)(o + 128 + cg_ * 4);
;                     na4 = *(const LAS f32x4*)(o + 256 + cg_ * 4); nb4 = *(const LAS f32x4*)(o + 320 + cg_ * 4);
;                     nvv = o[192 + rq * 16 + rloc];
;                 }
;                 __builtin_amdgcn_sched_barrier(0);
;                 typedef float f32x2_ __attribute__((ext_vector_type(2)));
;                 f32x2_ ta = (f32x2_){S[0], S[1]} * (f32x2_){a4[0], a4[1]}; ta = (f32x2_){S[2], S[3]} * (f32x2_){a4[2], a4[3]} + ta;
;                 f32x2_ ty = (f32x2_){S[0], S[1]} * (f32x2_){rp[0], rp[1]}; ty = (f32x2_){S[2], S[3]} * (f32x2_){rp[2], rp[3]} + ty;
;                 const f32x4 T = S * d4 + vv * k4;
;                 float sa = ta[0] + ta[1];
;                 float yp = ty[0] + ty[1];
;                 sa = dpp_add<0xB1>(sa); yp = dpp_add<0xB1>(yp);
;                 sa = dpp_add<0x4E>(sa); yp = dpp_add<0x4E>(yp);
;                 sa = dpp_add<0x124>(sa); yp = dpp_add<0x124>(yp);
;                 sa = dpp_add<0x128>(sa); yp = dpp_add<0x128>(yp);
;                 if (tk > 0) yk[(tk - 1) >> 4] = (cg_ == ((tk - 1) & 15)) ? yp : yk[(tk - 1) >> 4];
;                 S = sa * b4 + T;
;                 rp = r4;
;                 r4 = nr4; d4 = nd4; k4 = nk4; a4 = na4; b4 = nb4; vv = nvv;
;             }
	v_pk_mul_f32 v[190:191], v[190:191], v[196:197]
	v_pk_mul_f32 v[26:27], v[26:27], v[196:197]
	v_pk_fma_f32 v[188:189], v[188:189], v[34:35], v[190:191]
	v_pk_fma_f32 v[24:25], v[24:25], v[34:35], v[26:27]
	v_pk_mul_f32 v[26:27], v[180:181], v[34:35]
	v_add_f32_e32 v180, v188, v189
	v_add_f32_e32 v24, v24, v25
	v_pk_mul_f32 v[34:35], v[182:183], v[196:197]
	v_add_f32_dpp v25, v180, v180 quad_perm:[1,0,3,2] row_mask:0xf bank_mask:0xf bound_ctrl:1
	v_add_f32_dpp v24, v24, v24 quad_perm:[1,0,3,2] row_mask:0xf bank_mask:0xf bound_ctrl:1
	s_waitcnt lgkmcnt(6)
	v_pk_fma_f32 v[34:35], v[186:187], v[200:201], v[34:35] op_sel_hi:[1,0,1]
	v_add_f32_dpp v25, v25, v25 quad_perm:[2,3,0,1] row_mask:0xf bank_mask:0xf bound_ctrl:1
	v_add_f32_dpp v24, v24, v24 quad_perm:[2,3,0,1] row_mask:0xf bank_mask:0xf bound_ctrl:1
	v_pk_fma_f32 v[26:27], v[184:185], v[200:201], v[26:27] op_sel_hi:[1,0,1]
	v_add_f32_dpp v25, v25, v25 row_ror:4 row_mask:0xf bank_mask:0xf bound_ctrl:1
	v_add_f32_dpp v180, v24, v24 row_ror:4 row_mask:0xf bank_mask:0xf bound_ctrl:1
	s_nop 0
	v_add_f32_dpp v24, v25, v25 row_ror:8 row_mask:0xf bank_mask:0xf bound_ctrl:1
	v_add_f32_dpp v25, v180, v180 row_ror:8 row_mask:0xf bank_mask:0xf bound_ctrl:1
	v_cndmask_b32_e64 v199, v199, v25, s[10:11]
	v_pk_fma_f32 v[196:197], v[192:193], v[24:25], v[26:27] op_sel_hi:[1,0,1]
	v_pk_fma_f32 v[34:35], v[194:195], v[24:25], v[34:35] op_sel_hi:[1,0,1]
	ds_read_b128 v[24:27], v28 offset:7680
	ds_read_b128 v[180:183], v28 offset:7936
	ds_read_b128 v[184:187], v28 offset:8192
	ds_read_b128 v[188:191], v28 offset:8704
	ds_read_b128 v[192:195], v28 offset:8960
	ds_read_b32 v200, v29 offset:8448
	s_waitcnt lgkmcnt(8)
	v_pk_mul_f32 v[174:175], v[174:175], v[34:35]
	v_pk_mul_f32 v[32:33], v[32:33], v[34:35]
	v_pk_fma_f32 v[172:173], v[172:173], v[196:197], v[174:175]
	v_pk_fma_f32 v[30:31], v[30:31], v[196:197], v[32:33]
	v_pk_mul_f32 v[32:33], v[164:165], v[196:197]
	v_add_f32_e32 v164, v172, v173
	v_add_f32_e32 v30, v30, v31
	v_pk_mul_f32 v[34:35], v[166:167], v[34:35]
	v_add_f32_dpp v31, v164, v164 quad_perm:[1,0,3,2] row_mask:0xf bank_mask:0xf bound_ctrl:1
	v_add_f32_dpp v30, v30, v30 quad_perm:[1,0,3,2] row_mask:0xf bank_mask:0xf bound_ctrl:1
	s_waitcnt lgkmcnt(6)
	v_pk_fma_f32 v[34:35], v[170:171], v[198:199], v[34:35] op_sel_hi:[1,0,1]
	v_add_f32_dpp v31, v31, v31 quad_perm:[2,3,0,1] row_mask:0xf bank_mask:0xf bound_ctrl:1
	v_add_f32_dpp v30, v30, v30 quad_perm:[2,3,0,1] row_mask:0xf bank_mask:0xf bound_ctrl:1
	v_pk_fma_f32 v[32:33], v[168:169], v[198:199], v[32:33] op_sel_hi:[1,0,1]
	v_add_f32_dpp v31, v31, v31 row_ror:4 row_mask:0xf bank_mask:0xf bound_ctrl:1
	v_add_f32_dpp v164, v30, v30 row_ror:4 row_mask:0xf bank_mask:0xf bound_ctrl:1
	s_nop 0
	v_add_f32_dpp v30, v31, v31 row_ror:8 row_mask:0xf bank_mask:0xf bound_ctrl:1
	v_add_f32_dpp v31, v164, v164 row_ror:8 row_mask:0xf bank_mask:0xf bound_ctrl:1
	v_cndmask_b32_e64 v199, v199, v31, s[12:13]
	v_pk_fma_f32 v[196:197], v[176:177], v[30:31], v[32:33] op_sel_hi:[1,0,1]
	v_pk_fma_f32 v[34:35], v[178:179], v[30:31], v[34:35] op_sel_hi:[1,0,1]
	ds_read_b128 v[30:33], v28 offset:9216
	ds_read_b128 v[164:167], v28 offset:9472
	ds_read_b128 v[168:171], v28 offset:9728
	ds_read_b128 v[172:175], v28 offset:10240
	ds_read_b128 v[176:179], v28 offset:10496
	ds_read_b32 v198, v29 offset:9984
	s_waitcnt lgkmcnt(8)
	v_pk_mul_f32 v[190:191], v[190:191], v[34:35]
	v_pk_mul_f32 v[162:163], v[162:163], v[34:35]
	v_pk_fma_f32 v[188:189], v[188:189], v[196:197], v[190:191]
	v_pk_fma_f32 v[160:161], v[160:161], v[196:197], v[162:163]
	v_pk_mul_f32 v[162:163], v[180:181], v[196:197]
	v_add_f32_e32 v180, v188, v189
	v_add_f32_e32 v160, v160, v161
	v_pk_mul_f32 v[34:35], v[182:183], v[34:35]
	v_add_f32_dpp v161, v180, v180 quad_perm:[1,0,3,2] row_mask:0xf bank_mask:0xf bound_ctrl:1
	v_add_f32_dpp v160, v160, v160 quad_perm:[1,0,3,2] row_mask:0xf bank_mask:0xf bound_ctrl:1
	s_waitcnt lgkmcnt(6)
	v_pk_fma_f32 v[34:35], v[186:187], v[200:201], v[34:35] op_sel_hi:[1,0,1]
	v_add_f32_dpp v161, v161, v161 quad_perm:[2,3,0,1] row_mask:0xf bank_mask:0xf bound_ctrl:1
	v_add_f32_dpp v160, v160, v160 quad_perm:[2,3,0,1] row_mask:0xf bank_mask:0xf bound_ctrl:1
	v_pk_fma_f32 v[162:163], v[184:185], v[200:201], v[162:163] op_sel_hi:[1,0,1]
	v_add_f32_dpp v161, v161, v161 row_ror:4 row_mask:0xf bank_mask:0xf bound_ctrl:1
	v_add_f32_dpp v180, v160, v160 row_ror:4 row_mask:0xf bank_mask:0xf bound_ctrl:1
	s_nop 0
	v_add_f32_dpp v160, v161, v161 row_ror:8 row_mask:0xf bank_mask:0xf bound_ctrl:1
	v_add_f32_dpp v161, v180, v180 row_ror:8 row_mask:0xf bank_mask:0xf bound_ctrl:1
	v_cndmask_b32_e64 v199, v199, v161, s[14:15]
	v_pk_fma_f32 v[196:197], v[192:193], v[160:161], v[162:163] op_sel_hi:[1,0,1]
	v_pk_fma_f32 v[34:35], v[194:195], v[160:161], v[34:35] op_sel_hi:[1,0,1]
	ds_read_b128 v[160:163], v28 offset:10752
	ds_read_b128 v[180:183], v28 offset:11008
	ds_read_b128 v[184:187], v28 offset:11264
	ds_read_b128 v[188:191], v28 offset:11776
	ds_read_b128 v[192:195], v28 offset:12032
	ds_read_b32 v200, v29 offset:11520
	s_waitcnt lgkmcnt(8)
	v_pk_mul_f32 v[174:175], v[174:175], v[34:35]
	v_pk_mul_f32 v[26:27], v[26:27], v[34:35]
	v_pk_fma_f32 v[172:173], v[172:173], v[196:197], v[174:175]
	v_pk_fma_f32 v[24:25], v[24:25], v[196:197], v[26:27]
	v_pk_mul_f32 v[26:27], v[164:165], v[196:197]
	v_add_f32_e32 v164, v172, v173
	v_add_f32_e32 v24, v24, v25
	v_pk_mul_f32 v[34:35], v[166:167], v[34:35]
	v_add_f32_dpp v25, v164, v164 quad_perm:[1,0,3,2] row_mask:0xf bank_mask:0xf bound_ctrl:1
	v_add_f32_dpp v24, v24, v24 quad_perm:[1,0,3,2] row_mask:0xf bank_mask:0xf bound_ctrl:1
	s_waitcnt lgkmcnt(6)
; #define LAS __attribute__((address_space(3)))
; __device__ __forceinline__ void rwkv_scan_prompt(const Params& p, LAS unsigned char* lds, int bh, int rq) {
;     ...
;             const LAS float* ob = OPS + buf * TC * 6 * 64;
;             f32x4 r4 = *(const LAS f32x4*)(ob + cg_ * 4), d4 = *(const LAS f32x4*)(ob + 64 + cg_ * 4), k4 = *(const LAS f32x4*)(ob + 128 + cg_ * 4),
;                   a4 = *(const LAS f32x4*)(ob + 256 + cg_ * 4), b4 = *(const LAS f32x4*)(ob + 320 + cg_ * 4);
;             float vv = ob[192 + rq * 16 + rloc];
;             f32x4 rp = r4;
; #pragma unroll
;             for (int tk = 0; tk < TC; ++tk) {
;                 f32x4 nr4 = r4, nd4 = d4, nk4 = k4, na4 = a4, nb4 = b4; float nvv = vv;
;                 if (tk < TC - 1) {
;                     const LAS float* o = ob + (tk + 1) * 6 * 64;
;                     nr4 = *(const LAS f32x4*)(o + cg_ * 4); nd4 = *(const LAS f32x4*)(o + 64 + cg_ * 4); nk4 = *(const LAS f32x4*)(o + 128 + cg_ * 4);
;                     na4 = *(const LAS f32x4*)(o + 256 + cg_ * 4); nb4 = *(const LAS f32x4*)(o + 320 + cg_ * 4);
;                     nvv = o[192 + rq * 16 + rloc];
;                 }
;                 __builtin_amdgcn_sched_barrier(0);
;                 typedef float f32x2_ __attribute__((ext_vector_type(2)));
;                 f32x2_ ta = (f32x2_){S[0], S[1]} * (f32x2_){a4[0], a4[1]}; ta = (f32x2_){S[2], S[3]} * (f32x2_){a4[2], a4[3]} + ta;
;                 f32x2_ ty = (f32x2_){S[0], S[1]} * (f32x2_){rp[0], rp[1]}; ty = (f32x2_){S[2], S[3]} * (f32x2_){rp[2], rp[3]} + ty;
;                 const f32x4 T = S * d4 + vv * k4;
;                 float sa = ta[0] + ta[1];
;                 float yp = ty[0] + ty[1];
;                 sa = dpp_add<0xB1>(sa); yp = dpp_add<0xB1>(yp);
;                 sa = dpp_add<0x4E>(sa); yp = dpp_add<0x4E>(yp);
;                 sa = dpp_add<0x124>(sa); yp = dpp_add<0x124>(yp);
;                 sa = dpp_add<0x128>(sa); yp = dpp_add<0x128>(yp);
;                 if (tk > 0) yk[(tk - 1) >> 4] = (cg_ == ((tk - 1) & 15)) ? yp : yk[(tk - 1) >> 4];
;                 S = sa * b4 + T;
;                 rp = r4;
;                 r4 = nr4; d4 = nd4; k4 = nk4; a4 = na4; b4 = nb4; vv = nvv;
;             }
	v_pk_fma_f32 v[34:35], v[170:171], v[198:199], v[34:35] op_sel_hi:[1,0,1]
	v_add_f32_dpp v25, v25, v25 quad_perm:[2,3,0,1] row_mask:0xf bank_mask:0xf bound_ctrl:1
	v_add_f32_dpp v24, v24, v24 quad_perm:[2,3,0,1] row_mask:0xf bank_mask:0xf bound_ctrl:1
	v_pk_fma_f32 v[26:27], v[168:169], v[198:199], v[26:27] op_sel_hi:[1,0,1]
	v_add_f32_dpp v25, v25, v25 row_ror:4 row_mask:0xf bank_mask:0xf bound_ctrl:1
	v_add_f32_dpp v164, v24, v24 row_ror:4 row_mask:0xf bank_mask:0xf bound_ctrl:1
	s_nop 0
	v_add_f32_dpp v24, v25, v25 row_ror:8 row_mask:0xf bank_mask:0xf bound_ctrl:1
	v_add_f32_dpp v25, v164, v164 row_ror:8 row_mask:0xf bank_mask:0xf bound_ctrl:1
	v_cndmask_b32_e64 v199, v199, v25, s[16:17]
	v_pk_fma_f32 v[196:197], v[176:177], v[24:25], v[26:27] op_sel_hi:[1,0,1]
	v_pk_fma_f32 v[34:35], v[178:179], v[24:25], v[34:35] op_sel_hi:[1,0,1]
	ds_read_b128 v[24:27], v28 offset:12288
	ds_read_b128 v[164:167], v28 offset:12544
	ds_read_b128 v[168:171], v28 offset:12800
	ds_read_b128 v[172:175], v28 offset:13312
	ds_read_b128 v[176:179], v28 offset:13568
	ds_read_b32 v198, v29 offset:13056
	s_waitcnt lgkmcnt(8)
	v_pk_mul_f32 v[190:191], v[190:191], v[34:35]
	v_pk_mul_f32 v[32:33], v[32:33], v[34:35]
	v_pk_fma_f32 v[188:189], v[188:189], v[196:197], v[190:191]
	v_pk_fma_f32 v[30:31], v[30:31], v[196:197], v[32:33]
	v_pk_mul_f32 v[32:33], v[180:181], v[196:197]
	v_add_f32_e32 v180, v188, v189
	v_add_f32_e32 v30, v30, v31
	v_pk_mul_f32 v[34:35], v[182:183], v[34:35]
	v_add_f32_dpp v31, v180, v180 quad_perm:[1,0,3,2] row_mask:0xf bank_mask:0xf bound_ctrl:1
	v_add_f32_dpp v30, v30, v30 quad_perm:[1,0,3,2] row_mask:0xf bank_mask:0xf bound_ctrl:1
	s_waitcnt lgkmcnt(6)
	v_pk_fma_f32 v[34:35], v[186:187], v[200:201], v[34:35] op_sel_hi:[1,0,1]
	v_add_f32_dpp v31, v31, v31 quad_perm:[2,3,0,1] row_mask:0xf bank_mask:0xf bound_ctrl:1
	v_add_f32_dpp v30, v30, v30 quad_perm:[2,3,0,1] row_mask:0xf bank_mask:0xf bound_ctrl:1
	v_pk_fma_f32 v[32:33], v[184:185], v[200:201], v[32:33] op_sel_hi:[1,0,1]
	v_add_f32_dpp v31, v31, v31 row_ror:4 row_mask:0xf bank_mask:0xf bound_ctrl:1
	v_add_f32_dpp v180, v30, v30 row_ror:4 row_mask:0xf bank_mask:0xf bound_ctrl:1
	s_nop 0
	v_add_f32_dpp v30, v31, v31 row_ror:8 row_mask:0xf bank_mask:0xf bound_ctrl:1
	v_add_f32_dpp v31, v180, v180 row_ror:8 row_mask:0xf bank_mask:0xf bound_ctrl:1
	v_cndmask_b32_e64 v199, v199, v31, s[18:19]
	v_pk_fma_f32 v[196:197], v[192:193], v[30:31], v[32:33] op_sel_hi:[1,0,1]
	v_pk_fma_f32 v[34:35], v[194:195], v[30:31], v[34:35] op_sel_hi:[1,0,1]
	ds_read_b128 v[30:33], v28 offset:13824
	ds_read_b128 v[180:183], v28 offset:14080
	ds_read_b128 v[184:187], v28 offset:14336
	ds_read_b128 v[188:191], v28 offset:14848
	ds_read_b128 v[192:195], v28 offset:15104
	ds_read_b32 v200, v29 offset:14592
	s_waitcnt lgkmcnt(8)
	v_pk_mul_f32 v[174:175], v[174:175], v[34:35]
	v_pk_mul_f32 v[162:163], v[162:163], v[34:35]
	v_pk_fma_f32 v[172:173], v[172:173], v[196:197], v[174:175]
	v_pk_fma_f32 v[160:161], v[160:161], v[196:197], v[162:163]
	v_pk_mul_f32 v[162:163], v[164:165], v[196:197]
	v_add_f32_e32 v164, v172, v173
	v_add_f32_e32 v160, v160, v161
	v_pk_mul_f32 v[34:35], v[166:167], v[34:35]
	v_add_f32_dpp v161, v164, v164 quad_perm:[1,0,3,2] row_mask:0xf bank_mask:0xf bound_ctrl:1
	v_add_f32_dpp v160, v160, v160 quad_perm:[1,0,3,2] row_mask:0xf bank_mask:0xf bound_ctrl:1
	s_waitcnt lgkmcnt(6)
	v_pk_fma_f32 v[34:35], v[170:171], v[198:199], v[34:35] op_sel_hi:[1,0,1]
	v_add_f32_dpp v161, v161, v161 quad_perm:[2,3,0,1] row_mask:0xf bank_mask:0xf bound_ctrl:1
	v_add_f32_dpp v160, v160, v160 quad_perm:[2,3,0,1] row_mask:0xf bank_mask:0xf bound_ctrl:1
	v_pk_fma_f32 v[162:163], v[168:169], v[198:199], v[162:163] op_sel_hi:[1,0,1]
	v_add_f32_dpp v161, v161, v161 row_ror:4 row_mask:0xf bank_mask:0xf bound_ctrl:1
	v_add_f32_dpp v164, v160, v160 row_ror:4 row_mask:0xf bank_mask:0xf bound_ctrl:1
	s_nop 0
	v_add_f32_dpp v160, v161, v161 row_ror:8 row_mask:0xf bank_mask:0xf bound_ctrl:1
	v_add_f32_dpp v161, v164, v164 row_ror:8 row_mask:0xf bank_mask:0xf bound_ctrl:1
	v_cndmask_b32_e64 v199, v199, v161, s[20:21]
	v_pk_fma_f32 v[196:197], v[176:177], v[160:161], v[162:163] op_sel_hi:[1,0,1]
	v_pk_fma_f32 v[34:35], v[178:179], v[160:161], v[34:35] op_sel_hi:[1,0,1]
	ds_read_b128 v[160:163], v28 offset:15360
	ds_read_b128 v[164:167], v28 offset:15616
	ds_read_b128 v[168:171], v28 offset:15872
	ds_read_b128 v[172:175], v28 offset:16384
	ds_read_b128 v[176:179], v28 offset:16640
	ds_read_b32 v198, v29 offset:16128
	s_waitcnt lgkmcnt(8)
	v_pk_mul_f32 v[190:191], v[190:191], v[34:35]
	v_pk_mul_f32 v[26:27], v[26:27], v[34:35]
	v_pk_fma_f32 v[188:189], v[188:189], v[196:197], v[190:191]
	v_pk_fma_f32 v[24:25], v[24:25], v[196:197], v[26:27]
	v_pk_mul_f32 v[26:27], v[180:181], v[196:197]
	v_add_f32_e32 v180, v188, v189
	v_add_f32_e32 v24, v24, v25
	v_pk_mul_f32 v[34:35], v[182:183], v[34:35]
	v_add_f32_dpp v25, v180, v180 quad_perm:[1,0,3,2] row_mask:0xf bank_mask:0xf bound_ctrl:1
	v_add_f32_dpp v24, v24, v24 quad_perm:[1,0,3,2] row_mask:0xf bank_mask:0xf bound_ctrl:1
	s_waitcnt lgkmcnt(6)
; #define LAS __attribute__((address_space(3)))
; __device__ __forceinline__ void rwkv_scan_prompt(const Params& p, LAS unsigned char* lds, int bh, int rq) {
;     ...
;             const LAS float* ob = OPS + buf * TC * 6 * 64;
;             f32x4 r4 = *(const LAS f32x4*)(ob + cg_ * 4), d4 = *(const LAS f32x4*)(ob + 64 + cg_ * 4), k4 = *(const LAS f32x4*)(ob + 128 + cg_ * 4),
;                   a4 = *(const LAS f32x4*)(ob + 256 + cg_ * 4), b4 = *(const LAS f32x4*)(ob + 320 + cg_ * 4);
;             float vv = ob[192 + rq * 16 + rloc];
;             f32x4 rp = r4;
; #pragma unroll
;             for (int tk = 0; tk < TC; ++tk) {
;                 f32x4 nr4 = r4, nd4 = d4, nk4 = k4, na4 = a4, nb4 = b4; float nvv = vv;
;                 if (tk < TC - 1) {
;                     const LAS float* o = ob + (tk + 1) * 6 * 64;
;                     nr4 = *(const LAS f32x4*)(o + cg_ * 4); nd4 = *(const LAS f32x4*)(o + 64 + cg_ * 4); nk4 = *(const LAS f32x4*)(o + 128 + cg_ * 4);
;                     na4 = *(const LAS f32x4*)(o + 256 + cg_ * 4); nb4 = *(const LAS f32x4*)(o + 320 + cg_ * 4);
;                     nvv = o[192 + rq * 16 + rloc];
;                 }
;                 __builtin_amdgcn_sched_barrier(0);
;                 typedef float f32x2_ __attribute__((ext_vector_type(2)));
;                 f32x2_ ta = (f32x2_){S[0], S[1]} * (f32x2_){a4[0], a4[1]}; ta = (f32x2_){S[2], S[3]} * (f32x2_){a4[2], a4[3]} + ta;
;                 f32x2_ ty = (f32x2_){S[0], S[1]} * (f32x2_){rp[0], rp[1]}; ty = (f32x2_){S[2], S[3]} * (f32x2_){rp[2], rp[3]} + ty;
;                 const f32x4 T = S * d4 + vv * k4;
;                 float sa = ta[0] + ta[1];
;                 float yp = ty[0] + ty[1];
;                 sa = dpp_add<0xB1>(sa); yp = dpp_add<0xB1>(yp);
;                 sa = dpp_add<0x4E>(sa); yp = dpp_add<0x4E>(yp);
;                 sa = dpp_add<0x124>(sa); yp = dpp_add<0x124>(yp);
;                 sa = dpp_add<0x128>(sa); yp = dpp_add<0x128>(yp);
;                 if (tk > 0) yk[(tk - 1) >> 4] = (cg_ == ((tk - 1) & 15)) ? yp : yk[(tk - 1) >> 4];
;                 S = sa * b4 + T;
;                 rp = r4;
;                 r4 = nr4; d4 = nd4; k4 = nk4; a4 = na4; b4 = nb4; vv = nvv;
;             }
	v_pk_fma_f32 v[34:35], v[186:187], v[200:201], v[34:35] op_sel_hi:[1,0,1]
	v_add_f32_dpp v25, v25, v25 quad_perm:[2,3,0,1] row_mask:0xf bank_mask:0xf bound_ctrl:1
	v_add_f32_dpp v24, v24, v24 quad_perm:[2,3,0,1] row_mask:0xf bank_mask:0xf bound_ctrl:1
	v_pk_fma_f32 v[26:27], v[184:185], v[200:201], v[26:27] op_sel_hi:[1,0,1]
	v_add_f32_dpp v25, v25, v25 row_ror:4 row_mask:0xf bank_mask:0xf bound_ctrl:1
	v_add_f32_dpp v180, v24, v24 row_ror:4 row_mask:0xf bank_mask:0xf bound_ctrl:1
	s_nop 0
	v_add_f32_dpp v24, v25, v25 row_ror:8 row_mask:0xf bank_mask:0xf bound_ctrl:1
	v_add_f32_dpp v25, v180, v180 row_ror:8 row_mask:0xf bank_mask:0xf bound_ctrl:1
	v_cndmask_b32_e64 v199, v199, v25, s[22:23]
	v_pk_fma_f32 v[196:197], v[192:193], v[24:25], v[26:27] op_sel_hi:[1,0,1]
	v_pk_fma_f32 v[34:35], v[194:195], v[24:25], v[34:35] op_sel_hi:[1,0,1]
	ds_read_b128 v[24:27], v28 offset:16896
	ds_read_b128 v[180:183], v28 offset:17152
	ds_read_b128 v[184:187], v28 offset:17408
	ds_read_b128 v[188:191], v28 offset:17920
	ds_read_b128 v[192:195], v28 offset:18176
	ds_read_b32 v200, v29 offset:17664
	s_waitcnt lgkmcnt(8)
	v_pk_mul_f32 v[174:175], v[174:175], v[34:35]
	v_pk_mul_f32 v[32:33], v[32:33], v[34:35]
	v_pk_fma_f32 v[172:173], v[172:173], v[196:197], v[174:175]
	v_pk_fma_f32 v[30:31], v[30:31], v[196:197], v[32:33]
	v_pk_mul_f32 v[32:33], v[164:165], v[196:197]
	v_add_f32_e32 v164, v172, v173
	v_add_f32_e32 v30, v30, v31
	v_pk_mul_f32 v[34:35], v[166:167], v[34:35]
	v_add_f32_dpp v31, v164, v164 quad_perm:[1,0,3,2] row_mask:0xf bank_mask:0xf bound_ctrl:1
	v_add_f32_dpp v30, v30, v30 quad_perm:[1,0,3,2] row_mask:0xf bank_mask:0xf bound_ctrl:1
	s_waitcnt lgkmcnt(6)
	v_pk_fma_f32 v[34:35], v[170:171], v[198:199], v[34:35] op_sel_hi:[1,0,1]
	v_add_f32_dpp v31, v31, v31 quad_perm:[2,3,0,1] row_mask:0xf bank_mask:0xf bound_ctrl:1
	v_add_f32_dpp v30, v30, v30 quad_perm:[2,3,0,1] row_mask:0xf bank_mask:0xf bound_ctrl:1
	v_pk_fma_f32 v[32:33], v[168:169], v[198:199], v[32:33] op_sel_hi:[1,0,1]
	v_add_f32_dpp v31, v31, v31 row_ror:4 row_mask:0xf bank_mask:0xf bound_ctrl:1
	v_add_f32_dpp v164, v30, v30 row_ror:4 row_mask:0xf bank_mask:0xf bound_ctrl:1
	s_nop 0
	v_add_f32_dpp v30, v31, v31 row_ror:8 row_mask:0xf bank_mask:0xf bound_ctrl:1
	v_add_f32_dpp v31, v164, v164 row_ror:8 row_mask:0xf bank_mask:0xf bound_ctrl:1
	v_cndmask_b32_e64 v199, v199, v31, s[24:25]
	v_pk_fma_f32 v[196:197], v[176:177], v[30:31], v[32:33] op_sel_hi:[1,0,1]
	v_pk_fma_f32 v[34:35], v[178:179], v[30:31], v[34:35] op_sel_hi:[1,0,1]
	ds_read_b128 v[30:33], v28 offset:18432
	ds_read_b128 v[164:167], v28 offset:18688
	ds_read_b128 v[168:171], v28 offset:18944
	ds_read_b128 v[172:175], v28 offset:19456
	ds_read_b128 v[176:179], v28 offset:19712
	ds_read_b32 v198, v29 offset:19200
	s_waitcnt lgkmcnt(8)
	v_pk_mul_f32 v[190:191], v[190:191], v[34:35]
	v_pk_mul_f32 v[162:163], v[162:163], v[34:35]
	v_pk_fma_f32 v[188:189], v[188:189], v[196:197], v[190:191]
	v_pk_fma_f32 v[160:161], v[160:161], v[196:197], v[162:163]
	v_pk_mul_f32 v[162:163], v[180:181], v[196:197]
	v_add_f32_e32 v180, v188, v189
	v_add_f32_e32 v160, v160, v161
	v_pk_mul_f32 v[34:35], v[182:183], v[34:35]
	v_add_f32_dpp v161, v180, v180 quad_perm:[1,0,3,2] row_mask:0xf bank_mask:0xf bound_ctrl:1
	v_add_f32_dpp v160, v160, v160 quad_perm:[1,0,3,2] row_mask:0xf bank_mask:0xf bound_ctrl:1
	s_waitcnt lgkmcnt(6)
	v_pk_fma_f32 v[34:35], v[186:187], v[200:201], v[34:35] op_sel_hi:[1,0,1]
	v_add_f32_dpp v161, v161, v161 quad_perm:[2,3,0,1] row_mask:0xf bank_mask:0xf bound_ctrl:1
	v_add_f32_dpp v160, v160, v160 quad_perm:[2,3,0,1] row_mask:0xf bank_mask:0xf bound_ctrl:1
	v_pk_fma_f32 v[162:163], v[184:185], v[200:201], v[162:163] op_sel_hi:[1,0,1]
	v_add_f32_dpp v161, v161, v161 row_ror:4 row_mask:0xf bank_mask:0xf bound_ctrl:1
	v_add_f32_dpp v180, v160, v160 row_ror:4 row_mask:0xf bank_mask:0xf bound_ctrl:1
	s_nop 0
	v_add_f32_dpp v160, v161, v161 row_ror:8 row_mask:0xf bank_mask:0xf bound_ctrl:1
	v_add_f32_dpp v161, v180, v180 row_ror:8 row_mask:0xf bank_mask:0xf bound_ctrl:1
	v_cndmask_b32_e64 v199, v199, v161, s[26:27]
	v_pk_fma_f32 v[196:197], v[192:193], v[160:161], v[162:163] op_sel_hi:[1,0,1]
	v_pk_fma_f32 v[34:35], v[194:195], v[160:161], v[34:35] op_sel_hi:[1,0,1]
	ds_read_b128 v[160:163], v28 offset:19968
	ds_read_b128 v[180:183], v28 offset:20224
	ds_read_b128 v[184:187], v28 offset:20480
	ds_read_b128 v[188:191], v28 offset:20992
	ds_read_b128 v[192:195], v28 offset:21248
	ds_read_b32 v200, v29 offset:20736
	s_waitcnt lgkmcnt(8)
	v_pk_mul_f32 v[174:175], v[174:175], v[34:35]
	v_pk_mul_f32 v[26:27], v[26:27], v[34:35]
	v_pk_fma_f32 v[172:173], v[172:173], v[196:197], v[174:175]
	v_pk_fma_f32 v[24:25], v[24:25], v[196:197], v[26:27]
	v_pk_mul_f32 v[26:27], v[164:165], v[196:197]
	v_add_f32_e32 v164, v172, v173
	v_add_f32_e32 v24, v24, v25
	v_pk_mul_f32 v[34:35], v[166:167], v[34:35]
	v_add_f32_dpp v25, v164, v164 quad_perm:[1,0,3,2] row_mask:0xf bank_mask:0xf bound_ctrl:1
	v_add_f32_dpp v24, v24, v24 quad_perm:[1,0,3,2] row_mask:0xf bank_mask:0xf bound_ctrl:1
	s_waitcnt lgkmcnt(6)
; #define LAS __attribute__((address_space(3)))
; __device__ __forceinline__ void rwkv_scan_prompt(const Params& p, LAS unsigned char* lds, int bh, int rq) {
;     ...
;             const LAS float* ob = OPS + buf * TC * 6 * 64;
;             f32x4 r4 = *(const LAS f32x4*)(ob + cg_ * 4), d4 = *(const LAS f32x4*)(ob + 64 + cg_ * 4), k4 = *(const LAS f32x4*)(ob + 128 + cg_ * 4),
;                   a4 = *(const LAS f32x4*)(ob + 256 + cg_ * 4), b4 = *(const LAS f32x4*)(ob + 320 + cg_ * 4);
;             float vv = ob[192 + rq * 16 + rloc];
;             f32x4 rp = r4;
; #pragma unroll
;             for (int tk = 0; tk < TC; ++tk) {
;                 f32x4 nr4 = r4, nd4 = d4, nk4 = k4, na4 = a4, nb4 = b4; float nvv = vv;
;                 if (tk < TC - 1) {
;                     const LAS float* o = ob + (tk + 1) * 6 * 64;
;                     nr4 = *(const LAS f32x4*)(o + cg_ * 4); nd4 = *(const LAS f32x4*)(o + 64 + cg_ * 4); nk4 = *(const LAS f32x4*)(o + 128 + cg_ * 4);
;                     na4 = *(const LAS f32x4*)(o + 256 + cg_ * 4); nb4 = *(const LAS f32x4*)(o + 320 + cg_ * 4);
;                     nvv = o[192 + rq * 16 + rloc];
;                 }
;                 __builtin_amdgcn_sched_barrier(0);
;                 typedef float f32x2_ __attribute__((ext_vector_type(2)));
;                 f32x2_ ta = (f32x2_){S[0], S[1]} * (f32x2_){a4[0], a4[1]}; ta = (f32x2_){S[2], S[3]} * (f32x2_){a4[2], a4[3]} + ta;
;                 f32x2_ ty = (f32x2_){S[0], S[1]} * (f32x2_){rp[0], rp[1]}; ty = (f32x2_){S[2], S[3]} * (f32x2_){rp[2], rp[3]} + ty;
;                 const f32x4 T = S * d4 + vv * k4;
;                 float sa = ta[0] + ta[1];
;                 float yp = ty[0] + ty[1];
;                 sa = dpp_add<0xB1>(sa); yp = dpp_add<0xB1>(yp);
;                 sa = dpp_add<0x4E>(sa); yp = dpp_add<0x4E>(yp);
;                 sa = dpp_add<0x124>(sa); yp = dpp_add<0x124>(yp);
;                 sa = dpp_add<0x128>(sa); yp = dpp_add<0x128>(yp);
;                 if (tk > 0) yk[(tk - 1) >> 4] = (cg_ == ((tk - 1) & 15)) ? yp : yk[(tk - 1) >> 4];
;                 S = sa * b4 + T;
;                 rp = r4;
;                 r4 = nr4; d4 = nd4; k4 = nk4; a4 = na4; b4 = nb4; vv = nvv;
;             }
	v_pk_fma_f32 v[34:35], v[170:171], v[198:199], v[34:35] op_sel_hi:[1,0,1]
	v_add_f32_dpp v25, v25, v25 quad_perm:[2,3,0,1] row_mask:0xf bank_mask:0xf bound_ctrl:1
	v_add_f32_dpp v24, v24, v24 quad_perm:[2,3,0,1] row_mask:0xf bank_mask:0xf bound_ctrl:1
	v_pk_fma_f32 v[26:27], v[168:169], v[198:199], v[26:27] op_sel_hi:[1,0,1]
	v_add_f32_dpp v25, v25, v25 row_ror:4 row_mask:0xf bank_mask:0xf bound_ctrl:1
	v_add_f32_dpp v164, v24, v24 row_ror:4 row_mask:0xf bank_mask:0xf bound_ctrl:1
	s_nop 0
	v_add_f32_dpp v24, v25, v25 row_ror:8 row_mask:0xf bank_mask:0xf bound_ctrl:1
	v_add_f32_dpp v25, v164, v164 row_ror:8 row_mask:0xf bank_mask:0xf bound_ctrl:1
	v_cndmask_b32_e64 v199, v199, v25, s[28:29]
	v_pk_fma_f32 v[196:197], v[176:177], v[24:25], v[26:27] op_sel_hi:[1,0,1]
	v_pk_fma_f32 v[34:35], v[178:179], v[24:25], v[34:35] op_sel_hi:[1,0,1]
	ds_read_b128 v[24:27], v28 offset:21504
	ds_read_b128 v[164:167], v28 offset:21760
	ds_read_b128 v[168:171], v28 offset:22016
	ds_read_b128 v[172:175], v28 offset:22528
	ds_read_b128 v[176:179], v28 offset:22784
	ds_read_b32 v198, v29 offset:22272
	s_waitcnt lgkmcnt(8)
	v_pk_mul_f32 v[190:191], v[190:191], v[34:35]
	v_pk_mul_f32 v[32:33], v[32:33], v[34:35]
	v_pk_fma_f32 v[188:189], v[188:189], v[196:197], v[190:191]
	v_pk_fma_f32 v[30:31], v[30:31], v[196:197], v[32:33]
	v_pk_mul_f32 v[32:33], v[180:181], v[196:197]
	v_add_f32_e32 v180, v188, v189
	v_add_f32_e32 v30, v30, v31
	v_pk_mul_f32 v[34:35], v[182:183], v[34:35]
	v_add_f32_dpp v31, v180, v180 quad_perm:[1,0,3,2] row_mask:0xf bank_mask:0xf bound_ctrl:1
	v_add_f32_dpp v30, v30, v30 quad_perm:[1,0,3,2] row_mask:0xf bank_mask:0xf bound_ctrl:1
	s_waitcnt lgkmcnt(6)
	v_pk_fma_f32 v[34:35], v[186:187], v[200:201], v[34:35] op_sel_hi:[1,0,1]
	v_add_f32_dpp v31, v31, v31 quad_perm:[2,3,0,1] row_mask:0xf bank_mask:0xf bound_ctrl:1
	v_add_f32_dpp v30, v30, v30 quad_perm:[2,3,0,1] row_mask:0xf bank_mask:0xf bound_ctrl:1
	v_pk_fma_f32 v[32:33], v[184:185], v[200:201], v[32:33] op_sel_hi:[1,0,1]
	v_add_f32_dpp v31, v31, v31 row_ror:4 row_mask:0xf bank_mask:0xf bound_ctrl:1
	v_add_f32_dpp v180, v30, v30 row_ror:4 row_mask:0xf bank_mask:0xf bound_ctrl:1
	s_nop 0
	v_add_f32_dpp v30, v31, v31 row_ror:8 row_mask:0xf bank_mask:0xf bound_ctrl:1
	v_add_f32_dpp v31, v180, v180 row_ror:8 row_mask:0xf bank_mask:0xf bound_ctrl:1
	v_cndmask_b32_e64 v199, v199, v31, s[30:31]
	v_pk_fma_f32 v[196:197], v[192:193], v[30:31], v[32:33] op_sel_hi:[1,0,1]
	v_pk_fma_f32 v[34:35], v[194:195], v[30:31], v[34:35] op_sel_hi:[1,0,1]
	ds_read_b128 v[30:33], v28 offset:23040
	ds_read_b128 v[180:183], v28 offset:23296
	ds_read_b128 v[184:187], v28 offset:23552
	ds_read_b128 v[188:191], v28 offset:24064
	ds_read_b128 v[192:195], v28 offset:24320
	ds_read_b32 v200, v29 offset:23808
	s_waitcnt lgkmcnt(8)
	v_pk_mul_f32 v[174:175], v[174:175], v[34:35]
	v_pk_mul_f32 v[162:163], v[162:163], v[34:35]
	v_pk_fma_f32 v[172:173], v[172:173], v[196:197], v[174:175]
	v_pk_fma_f32 v[160:161], v[160:161], v[196:197], v[162:163]
	v_pk_mul_f32 v[162:163], v[164:165], v[196:197]
	v_add_f32_e32 v164, v172, v173
	v_add_f32_e32 v160, v160, v161
	v_pk_mul_f32 v[34:35], v[166:167], v[34:35]
	v_add_f32_dpp v161, v164, v164 quad_perm:[1,0,3,2] row_mask:0xf bank_mask:0xf bound_ctrl:1
	v_add_f32_dpp v160, v160, v160 quad_perm:[1,0,3,2] row_mask:0xf bank_mask:0xf bound_ctrl:1
	s_waitcnt lgkmcnt(6)
	v_pk_fma_f32 v[34:35], v[170:171], v[198:199], v[34:35] op_sel_hi:[1,0,1]
	v_add_f32_dpp v161, v161, v161 quad_perm:[2,3,0,1] row_mask:0xf bank_mask:0xf bound_ctrl:1
	v_add_f32_dpp v160, v160, v160 quad_perm:[2,3,0,1] row_mask:0xf bank_mask:0xf bound_ctrl:1
	v_pk_fma_f32 v[162:163], v[168:169], v[198:199], v[162:163] op_sel_hi:[1,0,1]
	v_add_f32_dpp v161, v161, v161 row_ror:4 row_mask:0xf bank_mask:0xf bound_ctrl:1
	v_add_f32_dpp v164, v160, v160 row_ror:4 row_mask:0xf bank_mask:0xf bound_ctrl:1
	s_nop 0
	v_add_f32_dpp v160, v161, v161 row_ror:8 row_mask:0xf bank_mask:0xf bound_ctrl:1
	v_add_f32_dpp v161, v164, v164 row_ror:8 row_mask:0xf bank_mask:0xf bound_ctrl:1
	v_cndmask_b32_e64 v199, v199, v161, s[34:35]
	v_pk_fma_f32 v[196:197], v[176:177], v[160:161], v[162:163] op_sel_hi:[1,0,1]
	v_pk_fma_f32 v[34:35], v[178:179], v[160:161], v[34:35] op_sel_hi:[1,0,1]
	ds_read_b128 v[160:163], v28 offset:24576
	ds_read_b128 v[164:167], v28 offset:24832
	ds_read_b128 v[168:171], v28 offset:25088
	ds_read_b128 v[172:175], v28 offset:25600
	ds_read_b128 v[176:179], v28 offset:25856
	ds_read_b32 v198, v29 offset:25344
	s_waitcnt lgkmcnt(8)
	v_pk_mul_f32 v[190:191], v[190:191], v[34:35]
	v_pk_mul_f32 v[26:27], v[26:27], v[34:35]
	v_pk_fma_f32 v[188:189], v[188:189], v[196:197], v[190:191]
	v_pk_fma_f32 v[24:25], v[24:25], v[196:197], v[26:27]
	v_pk_mul_f32 v[26:27], v[180:181], v[196:197]
	v_add_f32_e32 v180, v188, v189
	v_add_f32_e32 v24, v24, v25
	v_pk_mul_f32 v[34:35], v[182:183], v[34:35]
	v_add_f32_dpp v25, v180, v180 quad_perm:[1,0,3,2] row_mask:0xf bank_mask:0xf bound_ctrl:1
	v_add_f32_dpp v24, v24, v24 quad_perm:[1,0,3,2] row_mask:0xf bank_mask:0xf bound_ctrl:1
	s_waitcnt lgkmcnt(6)
; #define LAS __attribute__((address_space(3)))
; __device__ __forceinline__ void rwkv_scan_prompt(const Params& p, LAS unsigned char* lds, int bh, int rq) {
;     ...
;             const LAS float* ob = OPS + buf * TC * 6 * 64;
;             f32x4 r4 = *(const LAS f32x4*)(ob + cg_ * 4), d4 = *(const LAS f32x4*)(ob + 64 + cg_ * 4), k4 = *(const LAS f32x4*)(ob + 128 + cg_ * 4),
;                   a4 = *(const LAS f32x4*)(ob + 256 + cg_ * 4), b4 = *(const LAS f32x4*)(ob + 320 + cg_ * 4);
;             float vv = ob[192 + rq * 16 + rloc];
;             f32x4 rp = r4;
; #pragma unroll
;             for (int tk = 0; tk < TC; ++tk) {
;                 f32x4 nr4 = r4, nd4 = d4, nk4 = k4, na4 = a4, nb4 = b4; float nvv = vv;
;                 if (tk < TC - 1) {
;                     const LAS float* o = ob + (tk + 1) * 6 * 64;
;                     nr4 = *(const LAS f32x4*)(o + cg_ * 4); nd4 = *(const LAS f32x4*)(o + 64 + cg_ * 4); nk4 = *(const LAS f32x4*)(o + 128 + cg_ * 4);
;                     na4 = *(const LAS f32x4*)(o + 256 + cg_ * 4); nb4 = *(const LAS f32x4*)(o + 320 + cg_ * 4);
;                     nvv = o[192 + rq * 16 + rloc];
;                 }
;                 __builtin_amdgcn_sched_barrier(0);
;                 typedef float f32x2_ __attribute__((ext_vector_type(2)));
;                 f32x2_ ta = (f32x2_){S[0], S[1]} * (f32x2_){a4[0], a4[1]}; ta = (f32x2_){S[2], S[3]} * (f32x2_){a4[2], a4[3]} + ta;
;                 f32x2_ ty = (f32x2_){S[0], S[1]} * (f32x2_){rp[0], rp[1]}; ty = (f32x2_){S[2], S[3]} * (f32x2_){rp[2], rp[3]} + ty;
;                 const f32x4 T = S * d4 + vv * k4;
;                 float sa = ta[0] + ta[1];
;                 float yp = ty[0] + ty[1];
;                 sa = dpp_add<0xB1>(sa); yp = dpp_add<0xB1>(yp);
;                 sa = dpp_add<0x4E>(sa); yp = dpp_add<0x4E>(yp);
;                 sa = dpp_add<0x124>(sa); yp = dpp_add<0x124>(yp);
;                 sa = dpp_add<0x128>(sa); yp = dpp_add<0x128>(yp);
;                 if (tk > 0) yk[(tk - 1) >> 4] = (cg_ == ((tk - 1) & 15)) ? yp : yk[(tk - 1) >> 4];
;                 S = sa * b4 + T;
;                 rp = r4;
;                 r4 = nr4; d4 = nd4; k4 = nk4; a4 = na4; b4 = nb4; vv = nvv;
;             }
	v_pk_fma_f32 v[34:35], v[186:187], v[200:201], v[34:35] op_sel_hi:[1,0,1]
	v_add_f32_dpp v25, v25, v25 quad_perm:[2,3,0,1] row_mask:0xf bank_mask:0xf bound_ctrl:1
	v_add_f32_dpp v24, v24, v24 quad_perm:[2,3,0,1] row_mask:0xf bank_mask:0xf bound_ctrl:1
	v_pk_fma_f32 v[26:27], v[184:185], v[200:201], v[26:27] op_sel_hi:[1,0,1]
	v_add_f32_dpp v25, v25, v25 row_ror:4 row_mask:0xf bank_mask:0xf bound_ctrl:1
	v_add_f32_dpp v180, v24, v24 row_ror:4 row_mask:0xf bank_mask:0xf bound_ctrl:1
	s_nop 0
	v_add_f32_dpp v24, v25, v25 row_ror:8 row_mask:0xf bank_mask:0xf bound_ctrl:1
	v_add_f32_dpp v25, v180, v180 row_ror:8 row_mask:0xf bank_mask:0xf bound_ctrl:1
	v_cndmask_b32_e64 v199, v199, v25, s[36:37]
	v_pk_fma_f32 v[196:197], v[192:193], v[24:25], v[26:27] op_sel_hi:[1,0,1]
	v_pk_fma_f32 v[34:35], v[194:195], v[24:25], v[34:35] op_sel_hi:[1,0,1]
	ds_read_b128 v[24:27], v28 offset:26112
	ds_read_b128 v[180:183], v28 offset:26368
	ds_read_b128 v[184:187], v28 offset:26624
	ds_read_b128 v[188:191], v28 offset:27136
	ds_read_b128 v[192:195], v28 offset:27392
	ds_read_b32 v200, v29 offset:26880
	s_waitcnt lgkmcnt(8)
	v_pk_mul_f32 v[174:175], v[174:175], v[34:35]
	v_pk_mul_f32 v[32:33], v[32:33], v[34:35]
	v_pk_fma_f32 v[172:173], v[172:173], v[196:197], v[174:175]
	v_pk_fma_f32 v[30:31], v[30:31], v[196:197], v[32:33]
	v_pk_mul_f32 v[32:33], v[164:165], v[196:197]
	v_add_f32_e32 v164, v172, v173
	v_add_f32_e32 v30, v30, v31
	v_pk_mul_f32 v[34:35], v[166:167], v[34:35]
	v_add_f32_dpp v31, v164, v164 quad_perm:[1,0,3,2] row_mask:0xf bank_mask:0xf bound_ctrl:1
	v_add_f32_dpp v30, v30, v30 quad_perm:[1,0,3,2] row_mask:0xf bank_mask:0xf bound_ctrl:1
	s_waitcnt lgkmcnt(6)
	v_pk_fma_f32 v[34:35], v[170:171], v[198:199], v[34:35] op_sel_hi:[1,0,1]
	v_add_f32_dpp v31, v31, v31 quad_perm:[2,3,0,1] row_mask:0xf bank_mask:0xf bound_ctrl:1
	v_add_f32_dpp v30, v30, v30 quad_perm:[2,3,0,1] row_mask:0xf bank_mask:0xf bound_ctrl:1
	v_pk_fma_f32 v[32:33], v[168:169], v[198:199], v[32:33] op_sel_hi:[1,0,1]
	v_add_f32_dpp v31, v31, v31 row_ror:4 row_mask:0xf bank_mask:0xf bound_ctrl:1
	v_add_f32_dpp v30, v30, v30 row_ror:4 row_mask:0xf bank_mask:0xf bound_ctrl:1
	s_nop 0
	v_add_f32_dpp v164, v31, v31 row_ror:8 row_mask:0xf bank_mask:0xf bound_ctrl:1
	v_add_f32_dpp v30, v30, v30 row_ror:8 row_mask:0xf bank_mask:0xf bound_ctrl:1
	v_cndmask_b32_e64 v30, v199, v30, s[4:5]
	v_pk_fma_f32 v[196:197], v[176:177], v[164:165], v[32:33] op_sel_hi:[1,0,1]
	v_pk_fma_f32 v[198:199], v[178:179], v[164:165], v[34:35] op_sel_hi:[1,0,1]
	ds_read_b128 v[32:35], v28 offset:27648
	ds_read_b128 v[164:167], v28 offset:27904
	ds_read_b128 v[168:171], v28 offset:28160
	ds_read_b128 v[172:175], v28 offset:28672
	ds_read_b128 v[176:179], v28 offset:28928
	ds_read_b32 v202, v29 offset:28416
	s_waitcnt lgkmcnt(8)
	v_pk_mul_f32 v[190:191], v[190:191], v[198:199]
	v_pk_mul_f32 v[162:163], v[162:163], v[198:199]
	v_pk_fma_f32 v[188:189], v[188:189], v[196:197], v[190:191]
	v_pk_fma_f32 v[160:161], v[160:161], v[196:197], v[162:163]
	v_add_f32_e32 v31, v188, v189
	v_add_f32_e32 v160, v160, v161
	v_pk_mul_f32 v[162:163], v[180:181], v[196:197]
	v_add_f32_dpp v31, v31, v31 quad_perm:[1,0,3,2] row_mask:0xf bank_mask:0xf bound_ctrl:1
	v_add_f32_dpp v160, v160, v160 quad_perm:[1,0,3,2] row_mask:0xf bank_mask:0xf bound_ctrl:1
	v_pk_mul_f32 v[180:181], v[182:183], v[198:199]
	v_add_f32_dpp v31, v31, v31 quad_perm:[2,3,0,1] row_mask:0xf bank_mask:0xf bound_ctrl:1
	v_add_f32_dpp v160, v160, v160 quad_perm:[2,3,0,1] row_mask:0xf bank_mask:0xf bound_ctrl:1
	s_waitcnt lgkmcnt(6)
	v_pk_fma_f32 v[180:181], v[186:187], v[200:201], v[180:181] op_sel_hi:[1,0,1]
	v_add_f32_dpp v31, v31, v31 row_ror:4 row_mask:0xf bank_mask:0xf bound_ctrl:1
	v_pk_fma_f32 v[162:163], v[184:185], v[200:201], v[162:163] op_sel_hi:[1,0,1]
	v_add_f32_dpp v161, v160, v160 row_ror:4 row_mask:0xf bank_mask:0xf bound_ctrl:1
	v_add_f32_dpp v160, v31, v31 row_ror:8 row_mask:0xf bank_mask:0xf bound_ctrl:1
	v_pk_fma_f32 v[196:197], v[192:193], v[160:161], v[162:163] op_sel_hi:[1,0,1]
	v_add_f32_dpp v31, v161, v161 row_ror:8 row_mask:0xf bank_mask:0xf bound_ctrl:1
	v_pk_fma_f32 v[198:199], v[194:195], v[160:161], v[180:181] op_sel_hi:[1,0,1]
	ds_read_b128 v[160:163], v28 offset:29184
	ds_read_b128 v[180:183], v28 offset:29440
	ds_read_b128 v[184:187], v28 offset:29696
	ds_read_b128 v[188:191], v28 offset:30208
	ds_read_b128 v[192:195], v28 offset:30464
	ds_read_b32 v200, v29 offset:29952
	v_cndmask_b32_e64 v31, 0, v31, s[6:7]
	s_waitcnt lgkmcnt(8)
	v_pk_mul_f32 v[174:175], v[174:175], v[198:199]
	v_pk_mul_f32 v[26:27], v[26:27], v[198:199]
	v_pk_fma_f32 v[172:173], v[172:173], v[196:197], v[174:175]
	v_pk_fma_f32 v[24:25], v[24:25], v[196:197], v[26:27]
	v_pk_mul_f32 v[26:27], v[164:165], v[196:197]
	v_pk_mul_f32 v[164:165], v[166:167], v[198:199]
	v_add_f32_e32 v166, v172, v173
	v_add_f32_e32 v24, v24, v25
	s_waitcnt lgkmcnt(6)
	v_pk_fma_f32 v[164:165], v[170:171], v[202:203], v[164:165] op_sel_hi:[1,0,1]
	v_add_f32_dpp v25, v166, v166 quad_perm:[1,0,3,2] row_mask:0xf bank_mask:0xf bound_ctrl:1
	v_add_f32_dpp v24, v24, v24 quad_perm:[1,0,3,2] row_mask:0xf bank_mask:0xf bound_ctrl:1
	v_pk_fma_f32 v[26:27], v[168:169], v[202:203], v[26:27] op_sel_hi:[1,0,1]
	v_add_f32_dpp v25, v25, v25 quad_perm:[2,3,0,1] row_mask:0xf bank_mask:0xf bound_ctrl:1
	v_add_f32_dpp v24, v24, v24 quad_perm:[2,3,0,1] row_mask:0xf bank_mask:0xf bound_ctrl:1
	s_nop 0
	v_add_f32_dpp v25, v25, v25 row_ror:4 row_mask:0xf bank_mask:0xf bound_ctrl:1
	v_add_f32_dpp v166, v24, v24 row_ror:4 row_mask:0xf bank_mask:0xf bound_ctrl:1
	s_nop 0
	v_add_f32_dpp v24, v25, v25 row_ror:8 row_mask:0xf bank_mask:0xf bound_ctrl:1
	v_add_f32_dpp v25, v166, v166 row_ror:8 row_mask:0xf bank_mask:0xf bound_ctrl:1
	v_cndmask_b32_e64 v31, v31, v25, s[8:9]
	v_pk_fma_f32 v[196:197], v[176:177], v[24:25], v[26:27] op_sel_hi:[1,0,1]
	v_pk_fma_f32 v[198:199], v[178:179], v[24:25], v[164:165] op_sel_hi:[1,0,1]
	ds_read_b128 v[24:27], v28 offset:30720
	ds_read_b128 v[164:167], v28 offset:30976
	ds_read_b128 v[168:171], v28 offset:31232
	ds_read_b128 v[172:175], v28 offset:31744
	ds_read_b128 v[176:179], v28 offset:32000
	ds_read_b32 v202, v29 offset:31488
	s_waitcnt lgkmcnt(8)
; #define LAS __attribute__((address_space(3)))
; __device__ __forceinline__ void rwkv_scan_prompt(const Params& p, LAS unsigned char* lds, int bh, int rq) {
;     ...
;             const LAS float* ob = OPS + buf * TC * 6 * 64;
;             f32x4 r4 = *(const LAS f32x4*)(ob + cg_ * 4), d4 = *(const LAS f32x4*)(ob + 64 + cg_ * 4), k4 = *(const LAS f32x4*)(ob + 128 + cg_ * 4),
;                   a4 = *(const LAS f32x4*)(ob + 256 + cg_ * 4), b4 = *(const LAS f32x4*)(ob + 320 + cg_ * 4);
;             float vv = ob[192 + rq * 16 + rloc];
;             f32x4 rp = r4;
; #pragma unroll
;             for (int tk = 0; tk < TC; ++tk) {
;                 f32x4 nr4 = r4, nd4 = d4, nk4 = k4, na4 = a4, nb4 = b4; float nvv = vv;
;                 if (tk < TC - 1) {
;                     const LAS float* o = ob + (tk + 1) * 6 * 64;
;                     nr4 = *(const LAS f32x4*)(o + cg_ * 4); nd4 = *(const LAS f32x4*)(o + 64 + cg_ * 4); nk4 = *(const LAS f32x4*)(o + 128 + cg_ * 4);
;                     na4 = *(const LAS f32x4*)(o + 256 + cg_ * 4); nb4 = *(const LAS f32x4*)(o + 320 + cg_ * 4);
;                     nvv = o[192 + rq * 16 + rloc];
;                 }
;                 __builtin_amdgcn_sched_barrier(0);
;                 typedef float f32x2_ __attribute__((ext_vector_type(2)));
;                 f32x2_ ta = (f32x2_){S[0], S[1]} * (f32x2_){a4[0], a4[1]}; ta = (f32x2_){S[2], S[3]} * (f32x2_){a4[2], a4[3]} + ta;
;                 f32x2_ ty = (f32x2_){S[0], S[1]} * (f32x2_){rp[0], rp[1]}; ty = (f32x2_){S[2], S[3]} * (f32x2_){rp[2], rp[3]} + ty;
;                 const f32x4 T = S * d4 + vv * k4;
;                 float sa = ta[0] + ta[1];
;                 float yp = ty[0] + ty[1];
;                 sa = dpp_add<0xB1>(sa); yp = dpp_add<0xB1>(yp);
;                 sa = dpp_add<0x4E>(sa); yp = dpp_add<0x4E>(yp);
;                 sa = dpp_add<0x124>(sa); yp = dpp_add<0x124>(yp);
;                 sa = dpp_add<0x128>(sa); yp = dpp_add<0x128>(yp);
;                 if (tk > 0) yk[(tk - 1) >> 4] = (cg_ == ((tk - 1) & 15)) ? yp : yk[(tk - 1) >> 4];
;                 S = sa * b4 + T;
;                 rp = r4;
;                 r4 = nr4; d4 = nd4; k4 = nk4; a4 = na4; b4 = nb4; vv = nvv;
;             }
	v_pk_mul_f32 v[190:191], v[190:191], v[198:199]
	v_pk_mul_f32 v[34:35], v[34:35], v[198:199]
	v_pk_fma_f32 v[188:189], v[188:189], v[196:197], v[190:191]
	v_pk_fma_f32 v[32:33], v[32:33], v[196:197], v[34:35]
	v_pk_mul_f32 v[34:35], v[180:181], v[196:197]
	v_pk_mul_f32 v[180:181], v[182:183], v[198:199]
	v_add_f32_e32 v182, v188, v189
	v_add_f32_e32 v32, v32, v33
	s_waitcnt lgkmcnt(6)
	v_pk_fma_f32 v[180:181], v[186:187], v[200:201], v[180:181] op_sel_hi:[1,0,1]
	v_add_f32_dpp v33, v182, v182 quad_perm:[1,0,3,2] row_mask:0xf bank_mask:0xf bound_ctrl:1
	v_add_f32_dpp v32, v32, v32 quad_perm:[1,0,3,2] row_mask:0xf bank_mask:0xf bound_ctrl:1
	v_pk_fma_f32 v[34:35], v[184:185], v[200:201], v[34:35] op_sel_hi:[1,0,1]
	v_add_f32_dpp v33, v33, v33 quad_perm:[2,3,0,1] row_mask:0xf bank_mask:0xf bound_ctrl:1
	v_add_f32_dpp v32, v32, v32 quad_perm:[2,3,0,1] row_mask:0xf bank_mask:0xf bound_ctrl:1
	s_nop 0
	v_add_f32_dpp v33, v33, v33 row_ror:4 row_mask:0xf bank_mask:0xf bound_ctrl:1
	v_add_f32_dpp v182, v32, v32 row_ror:4 row_mask:0xf bank_mask:0xf bound_ctrl:1
	s_nop 0
	v_add_f32_dpp v32, v33, v33 row_ror:8 row_mask:0xf bank_mask:0xf bound_ctrl:1
	v_add_f32_dpp v33, v182, v182 row_ror:8 row_mask:0xf bank_mask:0xf bound_ctrl:1
	v_cndmask_b32_e64 v31, v31, v33, s[10:11]
	v_pk_fma_f32 v[196:197], v[192:193], v[32:33], v[34:35] op_sel_hi:[1,0,1]
	v_pk_fma_f32 v[198:199], v[194:195], v[32:33], v[180:181] op_sel_hi:[1,0,1]
	ds_read_b128 v[32:35], v28 offset:32256
	ds_read_b128 v[180:183], v28 offset:32512
	ds_read_b128 v[184:187], v28 offset:32768
	ds_read_b128 v[188:191], v28 offset:33280
	ds_read_b128 v[192:195], v28 offset:33536
	ds_read_b32 v200, v29 offset:33024
	s_waitcnt lgkmcnt(8)
	v_pk_mul_f32 v[174:175], v[174:175], v[198:199]
	v_pk_mul_f32 v[162:163], v[162:163], v[198:199]
	v_pk_fma_f32 v[172:173], v[172:173], v[196:197], v[174:175]
	v_pk_fma_f32 v[160:161], v[160:161], v[196:197], v[162:163]
	v_pk_mul_f32 v[162:163], v[164:165], v[196:197]
	v_pk_mul_f32 v[164:165], v[166:167], v[198:199]
	v_add_f32_e32 v166, v172, v173
	v_add_f32_e32 v160, v160, v161
	s_waitcnt lgkmcnt(6)
	v_pk_fma_f32 v[164:165], v[170:171], v[202:203], v[164:165] op_sel_hi:[1,0,1]
	v_add_f32_dpp v161, v166, v166 quad_perm:[1,0,3,2] row_mask:0xf bank_mask:0xf bound_ctrl:1
	v_add_f32_dpp v160, v160, v160 quad_perm:[1,0,3,2] row_mask:0xf bank_mask:0xf bound_ctrl:1
	v_pk_fma_f32 v[162:163], v[168:169], v[202:203], v[162:163] op_sel_hi:[1,0,1]
	v_add_f32_dpp v161, v161, v161 quad_perm:[2,3,0,1] row_mask:0xf bank_mask:0xf bound_ctrl:1
	v_add_f32_dpp v160, v160, v160 quad_perm:[2,3,0,1] row_mask:0xf bank_mask:0xf bound_ctrl:1
	s_nop 0
	v_add_f32_dpp v161, v161, v161 row_ror:4 row_mask:0xf bank_mask:0xf bound_ctrl:1
	v_add_f32_dpp v166, v160, v160 row_ror:4 row_mask:0xf bank_mask:0xf bound_ctrl:1
	s_nop 0
	v_add_f32_dpp v160, v161, v161 row_ror:8 row_mask:0xf bank_mask:0xf bound_ctrl:1
	v_add_f32_dpp v161, v166, v166 row_ror:8 row_mask:0xf bank_mask:0xf bound_ctrl:1
	v_cndmask_b32_e64 v31, v31, v161, s[12:13]
	v_pk_fma_f32 v[196:197], v[176:177], v[160:161], v[162:163] op_sel_hi:[1,0,1]
	v_pk_fma_f32 v[198:199], v[178:179], v[160:161], v[164:165] op_sel_hi:[1,0,1]
	ds_read_b128 v[160:163], v28 offset:33792
	ds_read_b128 v[164:167], v28 offset:34048
	ds_read_b128 v[168:171], v28 offset:34304
	ds_read_b128 v[172:175], v28 offset:34816
	ds_read_b128 v[176:179], v28 offset:35072
	ds_read_b32 v202, v29 offset:34560
	s_waitcnt lgkmcnt(8)
	v_pk_mul_f32 v[190:191], v[190:191], v[198:199]
	v_pk_mul_f32 v[26:27], v[26:27], v[198:199]
	v_pk_fma_f32 v[188:189], v[188:189], v[196:197], v[190:191]
	v_pk_fma_f32 v[24:25], v[24:25], v[196:197], v[26:27]
	v_pk_mul_f32 v[26:27], v[180:181], v[196:197]
	v_pk_mul_f32 v[180:181], v[182:183], v[198:199]
	v_add_f32_e32 v182, v188, v189
	v_add_f32_e32 v24, v24, v25
	s_waitcnt lgkmcnt(6)
	v_pk_fma_f32 v[180:181], v[186:187], v[200:201], v[180:181] op_sel_hi:[1,0,1]
	v_add_f32_dpp v25, v182, v182 quad_perm:[1,0,3,2] row_mask:0xf bank_mask:0xf bound_ctrl:1
	v_add_f32_dpp v24, v24, v24 quad_perm:[1,0,3,2] row_mask:0xf bank_mask:0xf bound_ctrl:1
	v_pk_fma_f32 v[26:27], v[184:185], v[200:201], v[26:27] op_sel_hi:[1,0,1]
	v_add_f32_dpp v25, v25, v25 quad_perm:[2,3,0,1] row_mask:0xf bank_mask:0xf bound_ctrl:1
	v_add_f32_dpp v24, v24, v24 quad_perm:[2,3,0,1] row_mask:0xf bank_mask:0xf bound_ctrl:1
	s_nop 0
	v_add_f32_dpp v25, v25, v25 row_ror:4 row_mask:0xf bank_mask:0xf bound_ctrl:1
	v_add_f32_dpp v182, v24, v24 row_ror:4 row_mask:0xf bank_mask:0xf bound_ctrl:1
	s_nop 0
	v_add_f32_dpp v24, v25, v25 row_ror:8 row_mask:0xf bank_mask:0xf bound_ctrl:1
	v_add_f32_dpp v25, v182, v182 row_ror:8 row_mask:0xf bank_mask:0xf bound_ctrl:1
	v_cndmask_b32_e64 v31, v31, v25, s[14:15]
	v_pk_fma_f32 v[196:197], v[192:193], v[24:25], v[26:27] op_sel_hi:[1,0,1]
	v_pk_fma_f32 v[198:199], v[194:195], v[24:25], v[180:181] op_sel_hi:[1,0,1]
	ds_read_b128 v[24:27], v28 offset:35328
	ds_read_b128 v[180:183], v28 offset:35584
	ds_read_b128 v[184:187], v28 offset:35840
	ds_read_b128 v[188:191], v28 offset:36352
	ds_read_b128 v[192:195], v28 offset:36608
	ds_read_b32 v200, v29 offset:36096
	s_waitcnt lgkmcnt(8)
	v_pk_mul_f32 v[174:175], v[174:175], v[198:199]
	v_pk_mul_f32 v[34:35], v[34:35], v[198:199]
	v_pk_fma_f32 v[172:173], v[172:173], v[196:197], v[174:175]
	v_pk_fma_f32 v[32:33], v[32:33], v[196:197], v[34:35]
	v_pk_mul_f32 v[34:35], v[164:165], v[196:197]
	v_pk_mul_f32 v[164:165], v[166:167], v[198:199]
	v_add_f32_e32 v166, v172, v173
	v_add_f32_e32 v32, v32, v33
	s_waitcnt lgkmcnt(6)
; #define LAS __attribute__((address_space(3)))
; __device__ __forceinline__ void rwkv_scan_prompt(const Params& p, LAS unsigned char* lds, int bh, int rq) {
;     ...
;             const LAS float* ob = OPS + buf * TC * 6 * 64;
;             f32x4 r4 = *(const LAS f32x4*)(ob + cg_ * 4), d4 = *(const LAS f32x4*)(ob + 64 + cg_ * 4), k4 = *(const LAS f32x4*)(ob + 128 + cg_ * 4),
;                   a4 = *(const LAS f32x4*)(ob + 256 + cg_ * 4), b4 = *(const LAS f32x4*)(ob + 320 + cg_ * 4);
;             float vv = ob[192 + rq * 16 + rloc];
;             f32x4 rp = r4;
; #pragma unroll
;             for (int tk = 0; tk < TC; ++tk) {
;                 f32x4 nr4 = r4, nd4 = d4, nk4 = k4, na4 = a4, nb4 = b4; float nvv = vv;
;                 if (tk < TC - 1) {
;                     const LAS float* o = ob + (tk + 1) * 6 * 64;
;                     nr4 = *(const LAS f32x4*)(o + cg_ * 4); nd4 = *(const LAS f32x4*)(o + 64 + cg_ * 4); nk4 = *(const LAS f32x4*)(o + 128 + cg_ * 4);
;                     na4 = *(const LAS f32x4*)(o + 256 + cg_ * 4); nb4 = *(const LAS f32x4*)(o + 320 + cg_ * 4);
;                     nvv = o[192 + rq * 16 + rloc];
;                 }
;                 __builtin_amdgcn_sched_barrier(0);
;                 typedef float f32x2_ __attribute__((ext_vector_type(2)));
;                 f32x2_ ta = (f32x2_){S[0], S[1]} * (f32x2_){a4[0], a4[1]}; ta = (f32x2_){S[2], S[3]} * (f32x2_){a4[2], a4[3]} + ta;
;                 f32x2_ ty = (f32x2_){S[0], S[1]} * (f32x2_){rp[0], rp[1]}; ty = (f32x2_){S[2], S[3]} * (f32x2_){rp[2], rp[3]} + ty;
;                 const f32x4 T = S * d4 + vv * k4;
;                 float sa = ta[0] + ta[1];
;                 float yp = ty[0] + ty[1];
;                 sa = dpp_add<0xB1>(sa); yp = dpp_add<0xB1>(yp);
;                 sa = dpp_add<0x4E>(sa); yp = dpp_add<0x4E>(yp);
;                 sa = dpp_add<0x124>(sa); yp = dpp_add<0x124>(yp);
;                 sa = dpp_add<0x128>(sa); yp = dpp_add<0x128>(yp);
;                 if (tk > 0) yk[(tk - 1) >> 4] = (cg_ == ((tk - 1) & 15)) ? yp : yk[(tk - 1) >> 4];
;                 S = sa * b4 + T;
;                 rp = r4;
;                 r4 = nr4; d4 = nd4; k4 = nk4; a4 = na4; b4 = nb4; vv = nvv;
;             }
	v_pk_fma_f32 v[164:165], v[170:171], v[202:203], v[164:165] op_sel_hi:[1,0,1]
	v_add_f32_dpp v33, v166, v166 quad_perm:[1,0,3,2] row_mask:0xf bank_mask:0xf bound_ctrl:1
	v_add_f32_dpp v32, v32, v32 quad_perm:[1,0,3,2] row_mask:0xf bank_mask:0xf bound_ctrl:1
	v_pk_fma_f32 v[34:35], v[168:169], v[202:203], v[34:35] op_sel_hi:[1,0,1]
	v_add_f32_dpp v33, v33, v33 quad_perm:[2,3,0,1] row_mask:0xf bank_mask:0xf bound_ctrl:1
	v_add_f32_dpp v32, v32, v32 quad_perm:[2,3,0,1] row_mask:0xf bank_mask:0xf bound_ctrl:1
	s_nop 0
	v_add_f32_dpp v33, v33, v33 row_ror:4 row_mask:0xf bank_mask:0xf bound_ctrl:1
	v_add_f32_dpp v166, v32, v32 row_ror:4 row_mask:0xf bank_mask:0xf bound_ctrl:1
	s_nop 0
	v_add_f32_dpp v32, v33, v33 row_ror:8 row_mask:0xf bank_mask:0xf bound_ctrl:1
	v_add_f32_dpp v33, v166, v166 row_ror:8 row_mask:0xf bank_mask:0xf bound_ctrl:1
	v_cndmask_b32_e64 v31, v31, v33, s[16:17]
	v_pk_fma_f32 v[196:197], v[176:177], v[32:33], v[34:35] op_sel_hi:[1,0,1]
	v_pk_fma_f32 v[198:199], v[178:179], v[32:33], v[164:165] op_sel_hi:[1,0,1]
	ds_read_b128 v[32:35], v28 offset:36864
	ds_read_b128 v[164:167], v28 offset:37120
	ds_read_b128 v[168:171], v28 offset:37376
	ds_read_b128 v[172:175], v28 offset:37888
	ds_read_b128 v[176:179], v28 offset:38144
	ds_read_b32 v202, v29 offset:37632
	s_waitcnt lgkmcnt(8)
	v_pk_mul_f32 v[190:191], v[190:191], v[198:199]
	v_pk_mul_f32 v[162:163], v[162:163], v[198:199]
	v_pk_fma_f32 v[188:189], v[188:189], v[196:197], v[190:191]
	v_pk_fma_f32 v[160:161], v[160:161], v[196:197], v[162:163]
	v_pk_mul_f32 v[162:163], v[180:181], v[196:197]
	v_pk_mul_f32 v[180:181], v[182:183], v[198:199]
	v_add_f32_e32 v182, v188, v189
	v_add_f32_e32 v160, v160, v161
	s_waitcnt lgkmcnt(6)
	v_pk_fma_f32 v[180:181], v[186:187], v[200:201], v[180:181] op_sel_hi:[1,0,1]
	v_add_f32_dpp v161, v182, v182 quad_perm:[1,0,3,2] row_mask:0xf bank_mask:0xf bound_ctrl:1
	v_add_f32_dpp v160, v160, v160 quad_perm:[1,0,3,2] row_mask:0xf bank_mask:0xf bound_ctrl:1
	v_pk_fma_f32 v[162:163], v[184:185], v[200:201], v[162:163] op_sel_hi:[1,0,1]
	v_add_f32_dpp v161, v161, v161 quad_perm:[2,3,0,1] row_mask:0xf bank_mask:0xf bound_ctrl:1
	v_add_f32_dpp v160, v160, v160 quad_perm:[2,3,0,1] row_mask:0xf bank_mask:0xf bound_ctrl:1
	s_nop 0
	v_add_f32_dpp v161, v161, v161 row_ror:4 row_mask:0xf bank_mask:0xf bound_ctrl:1
	v_add_f32_dpp v182, v160, v160 row_ror:4 row_mask:0xf bank_mask:0xf bound_ctrl:1
	s_nop 0
	v_add_f32_dpp v160, v161, v161 row_ror:8 row_mask:0xf bank_mask:0xf bound_ctrl:1
	v_add_f32_dpp v161, v182, v182 row_ror:8 row_mask:0xf bank_mask:0xf bound_ctrl:1
	v_cndmask_b32_e64 v31, v31, v161, s[18:19]
	v_pk_fma_f32 v[196:197], v[192:193], v[160:161], v[162:163] op_sel_hi:[1,0,1]
	v_pk_fma_f32 v[198:199], v[194:195], v[160:161], v[180:181] op_sel_hi:[1,0,1]
	ds_read_b128 v[160:163], v28 offset:38400
	ds_read_b128 v[180:183], v28 offset:38656
	ds_read_b128 v[184:187], v28 offset:38912
	ds_read_b128 v[188:191], v28 offset:39424
	ds_read_b128 v[192:195], v28 offset:39680
	ds_read_b32 v200, v29 offset:39168
	s_waitcnt lgkmcnt(8)
	v_pk_mul_f32 v[174:175], v[174:175], v[198:199]
	v_pk_mul_f32 v[26:27], v[26:27], v[198:199]
	v_pk_fma_f32 v[172:173], v[172:173], v[196:197], v[174:175]
	v_pk_fma_f32 v[24:25], v[24:25], v[196:197], v[26:27]
	v_pk_mul_f32 v[26:27], v[164:165], v[196:197]
	v_pk_mul_f32 v[164:165], v[166:167], v[198:199]
	v_add_f32_e32 v166, v172, v173
	v_add_f32_e32 v24, v24, v25
	s_waitcnt lgkmcnt(6)
	v_pk_fma_f32 v[164:165], v[170:171], v[202:203], v[164:165] op_sel_hi:[1,0,1]
	v_add_f32_dpp v25, v166, v166 quad_perm:[1,0,3,2] row_mask:0xf bank_mask:0xf bound_ctrl:1
	v_add_f32_dpp v24, v24, v24 quad_perm:[1,0,3,2] row_mask:0xf bank_mask:0xf bound_ctrl:1
	v_pk_fma_f32 v[26:27], v[168:169], v[202:203], v[26:27] op_sel_hi:[1,0,1]
	v_add_f32_dpp v25, v25, v25 quad_perm:[2,3,0,1] row_mask:0xf bank_mask:0xf bound_ctrl:1
	v_add_f32_dpp v24, v24, v24 quad_perm:[2,3,0,1] row_mask:0xf bank_mask:0xf bound_ctrl:1
	s_nop 0
	v_add_f32_dpp v25, v25, v25 row_ror:4 row_mask:0xf bank_mask:0xf bound_ctrl:1
	v_add_f32_dpp v166, v24, v24 row_ror:4 row_mask:0xf bank_mask:0xf bound_ctrl:1
	s_nop 0
	v_add_f32_dpp v24, v25, v25 row_ror:8 row_mask:0xf bank_mask:0xf bound_ctrl:1
	v_add_f32_dpp v25, v166, v166 row_ror:8 row_mask:0xf bank_mask:0xf bound_ctrl:1
	v_cndmask_b32_e64 v31, v31, v25, s[20:21]
	v_pk_fma_f32 v[196:197], v[176:177], v[24:25], v[26:27] op_sel_hi:[1,0,1]
	v_pk_fma_f32 v[198:199], v[178:179], v[24:25], v[164:165] op_sel_hi:[1,0,1]
	ds_read_b128 v[24:27], v28 offset:39936
	ds_read_b128 v[164:167], v28 offset:40192
	ds_read_b128 v[168:171], v28 offset:40448
	ds_read_b128 v[172:175], v28 offset:40960
	ds_read_b128 v[176:179], v28 offset:41216
	ds_read_b32 v202, v29 offset:40704
	s_waitcnt lgkmcnt(8)
	v_pk_mul_f32 v[190:191], v[190:191], v[198:199]
	v_pk_mul_f32 v[34:35], v[34:35], v[198:199]
	v_pk_fma_f32 v[188:189], v[188:189], v[196:197], v[190:191]
	v_pk_fma_f32 v[32:33], v[32:33], v[196:197], v[34:35]
	v_pk_mul_f32 v[34:35], v[180:181], v[196:197]
	v_pk_mul_f32 v[180:181], v[182:183], v[198:199]
	v_add_f32_e32 v182, v188, v189
	v_add_f32_e32 v32, v32, v33
	s_waitcnt lgkmcnt(6)
; #define LAS __attribute__((address_space(3)))
; __device__ __forceinline__ void rwkv_scan_prompt(const Params& p, LAS unsigned char* lds, int bh, int rq) {
;     ...
;             const LAS float* ob = OPS + buf * TC * 6 * 64;
;             f32x4 r4 = *(const LAS f32x4*)(ob + cg_ * 4), d4 = *(const LAS f32x4*)(ob + 64 + cg_ * 4), k4 = *(const LAS f32x4*)(ob + 128 + cg_ * 4),
;                   a4 = *(const LAS f32x4*)(ob + 256 + cg_ * 4), b4 = *(const LAS f32x4*)(ob + 320 + cg_ * 4);
;             float vv = ob[192 + rq * 16 + rloc];
;             f32x4 rp = r4;
; #pragma unroll
;             for (int tk = 0; tk < TC; ++tk) {
;                 f32x4 nr4 = r4, nd4 = d4, nk4 = k4, na4 = a4, nb4 = b4; float nvv = vv;
;                 if (tk < TC - 1) {
;                     const LAS float* o = ob + (tk + 1) * 6 * 64;
;                     nr4 = *(const LAS f32x4*)(o + cg_ * 4); nd4 = *(const LAS f32x4*)(o + 64 + cg_ * 4); nk4 = *(const LAS f32x4*)(o + 128 + cg_ * 4);
;                     na4 = *(const LAS f32x4*)(o + 256 + cg_ * 4); nb4 = *(const LAS f32x4*)(o + 320 + cg_ * 4);
;                     nvv = o[192 + rq * 16 + rloc];
;                 }
;                 __builtin_amdgcn_sched_barrier(0);
;                 typedef float f32x2_ __attribute__((ext_vector_type(2)));
;                 f32x2_ ta = (f32x2_){S[0], S[1]} * (f32x2_){a4[0], a4[1]}; ta = (f32x2_){S[2], S[3]} * (f32x2_){a4[2], a4[3]} + ta;
;                 f32x2_ ty = (f32x2_){S[0], S[1]} * (f32x2_){rp[0], rp[1]}; ty = (f32x2_){S[2], S[3]} * (f32x2_){rp[2], rp[3]} + ty;
;                 const f32x4 T = S * d4 + vv * k4;
;                 float sa = ta[0] + ta[1];
;                 float yp = ty[0] + ty[1];
;                 sa = dpp_add<0xB1>(sa); yp = dpp_add<0xB1>(yp);
;                 sa = dpp_add<0x4E>(sa); yp = dpp_add<0x4E>(yp);
;                 sa = dpp_add<0x124>(sa); yp = dpp_add<0x124>(yp);
;                 sa = dpp_add<0x128>(sa); yp = dpp_add<0x128>(yp);
;                 if (tk > 0) yk[(tk - 1) >> 4] = (cg_ == ((tk - 1) & 15)) ? yp : yk[(tk - 1) >> 4];
;                 S = sa * b4 + T;
;                 rp = r4;
;                 r4 = nr4; d4 = nd4; k4 = nk4; a4 = na4; b4 = nb4; vv = nvv;
;             }
	v_pk_fma_f32 v[180:181], v[186:187], v[200:201], v[180:181] op_sel_hi:[1,0,1]
	v_add_f32_dpp v33, v182, v182 quad_perm:[1,0,3,2] row_mask:0xf bank_mask:0xf bound_ctrl:1
	v_add_f32_dpp v32, v32, v32 quad_perm:[1,0,3,2] row_mask:0xf bank_mask:0xf bound_ctrl:1
	v_pk_fma_f32 v[34:35], v[184:185], v[200:201], v[34:35] op_sel_hi:[1,0,1]
	v_add_f32_dpp v33, v33, v33 quad_perm:[2,3,0,1] row_mask:0xf bank_mask:0xf bound_ctrl:1
	v_add_f32_dpp v32, v32, v32 quad_perm:[2,3,0,1] row_mask:0xf bank_mask:0xf bound_ctrl:1
	s_nop 0
	v_add_f32_dpp v33, v33, v33 row_ror:4 row_mask:0xf bank_mask:0xf bound_ctrl:1
	v_add_f32_dpp v182, v32, v32 row_ror:4 row_mask:0xf bank_mask:0xf bound_ctrl:1
	s_nop 0
	v_add_f32_dpp v32, v33, v33 row_ror:8 row_mask:0xf bank_mask:0xf bound_ctrl:1
	v_add_f32_dpp v33, v182, v182 row_ror:8 row_mask:0xf bank_mask:0xf bound_ctrl:1
	v_cndmask_b32_e64 v31, v31, v33, s[22:23]
	v_pk_fma_f32 v[196:197], v[192:193], v[32:33], v[34:35] op_sel_hi:[1,0,1]
	v_pk_fma_f32 v[198:199], v[194:195], v[32:33], v[180:181] op_sel_hi:[1,0,1]
	ds_read_b128 v[32:35], v28 offset:41472
	ds_read_b128 v[180:183], v28 offset:41728
	ds_read_b128 v[184:187], v28 offset:41984
	ds_read_b128 v[188:191], v28 offset:42496
	ds_read_b128 v[192:195], v28 offset:42752
	ds_read_b32 v200, v29 offset:42240
	s_waitcnt lgkmcnt(8)
	v_pk_mul_f32 v[174:175], v[174:175], v[198:199]
	v_pk_mul_f32 v[162:163], v[162:163], v[198:199]
	v_pk_fma_f32 v[172:173], v[172:173], v[196:197], v[174:175]
	v_pk_fma_f32 v[160:161], v[160:161], v[196:197], v[162:163]
	v_pk_mul_f32 v[162:163], v[164:165], v[196:197]
	v_pk_mul_f32 v[164:165], v[166:167], v[198:199]
	v_add_f32_e32 v166, v172, v173
	v_add_f32_e32 v160, v160, v161
	s_waitcnt lgkmcnt(6)
	v_pk_fma_f32 v[164:165], v[170:171], v[202:203], v[164:165] op_sel_hi:[1,0,1]
	v_add_f32_dpp v161, v166, v166 quad_perm:[1,0,3,2] row_mask:0xf bank_mask:0xf bound_ctrl:1
	v_add_f32_dpp v160, v160, v160 quad_perm:[1,0,3,2] row_mask:0xf bank_mask:0xf bound_ctrl:1
	v_pk_fma_f32 v[162:163], v[168:169], v[202:203], v[162:163] op_sel_hi:[1,0,1]
	v_add_f32_dpp v161, v161, v161 quad_perm:[2,3,0,1] row_mask:0xf bank_mask:0xf bound_ctrl:1
	v_add_f32_dpp v160, v160, v160 quad_perm:[2,3,0,1] row_mask:0xf bank_mask:0xf bound_ctrl:1
	s_nop 0
	v_add_f32_dpp v161, v161, v161 row_ror:4 row_mask:0xf bank_mask:0xf bound_ctrl:1
	v_add_f32_dpp v166, v160, v160 row_ror:4 row_mask:0xf bank_mask:0xf bound_ctrl:1
	s_nop 0
	v_add_f32_dpp v160, v161, v161 row_ror:8 row_mask:0xf bank_mask:0xf bound_ctrl:1
	v_add_f32_dpp v161, v166, v166 row_ror:8 row_mask:0xf bank_mask:0xf bound_ctrl:1
	v_cndmask_b32_e64 v31, v31, v161, s[24:25]
	v_pk_fma_f32 v[196:197], v[176:177], v[160:161], v[162:163] op_sel_hi:[1,0,1]
	v_pk_fma_f32 v[198:199], v[178:179], v[160:161], v[164:165] op_sel_hi:[1,0,1]
	ds_read_b128 v[160:163], v28 offset:43008
	ds_read_b128 v[164:167], v28 offset:43264
	ds_read_b128 v[168:171], v28 offset:43520
	ds_read_b128 v[172:175], v28 offset:44032
	ds_read_b128 v[176:179], v28 offset:44288
	ds_read_b32 v202, v29 offset:43776
	s_waitcnt lgkmcnt(8)
	v_pk_mul_f32 v[190:191], v[190:191], v[198:199]
	v_pk_mul_f32 v[26:27], v[26:27], v[198:199]
	v_pk_fma_f32 v[188:189], v[188:189], v[196:197], v[190:191]
	v_pk_fma_f32 v[24:25], v[24:25], v[196:197], v[26:27]
	v_pk_mul_f32 v[26:27], v[180:181], v[196:197]
	v_pk_mul_f32 v[180:181], v[182:183], v[198:199]
	v_add_f32_e32 v182, v188, v189
	v_add_f32_e32 v24, v24, v25
	s_waitcnt lgkmcnt(6)
	v_pk_fma_f32 v[180:181], v[186:187], v[200:201], v[180:181] op_sel_hi:[1,0,1]
	v_add_f32_dpp v25, v182, v182 quad_perm:[1,0,3,2] row_mask:0xf bank_mask:0xf bound_ctrl:1
	v_add_f32_dpp v24, v24, v24 quad_perm:[1,0,3,2] row_mask:0xf bank_mask:0xf bound_ctrl:1
	v_pk_fma_f32 v[26:27], v[184:185], v[200:201], v[26:27] op_sel_hi:[1,0,1]
	v_add_f32_dpp v25, v25, v25 quad_perm:[2,3,0,1] row_mask:0xf bank_mask:0xf bound_ctrl:1
	v_add_f32_dpp v24, v24, v24 quad_perm:[2,3,0,1] row_mask:0xf bank_mask:0xf bound_ctrl:1
	s_nop 0
	v_add_f32_dpp v25, v25, v25 row_ror:4 row_mask:0xf bank_mask:0xf bound_ctrl:1
	v_add_f32_dpp v182, v24, v24 row_ror:4 row_mask:0xf bank_mask:0xf bound_ctrl:1
	s_nop 0
	v_add_f32_dpp v24, v25, v25 row_ror:8 row_mask:0xf bank_mask:0xf bound_ctrl:1
	v_add_f32_dpp v25, v182, v182 row_ror:8 row_mask:0xf bank_mask:0xf bound_ctrl:1
	v_cndmask_b32_e64 v31, v31, v25, s[26:27]
	v_pk_fma_f32 v[196:197], v[192:193], v[24:25], v[26:27] op_sel_hi:[1,0,1]
	v_pk_fma_f32 v[198:199], v[194:195], v[24:25], v[180:181] op_sel_hi:[1,0,1]
	ds_read_b128 v[24:27], v28 offset:44544
	ds_read_b128 v[180:183], v28 offset:44800
	ds_read_b128 v[184:187], v28 offset:45056
	ds_read_b128 v[188:191], v28 offset:45568
	ds_read_b128 v[192:195], v28 offset:45824
	ds_read_b32 v200, v29 offset:45312
	s_waitcnt lgkmcnt(8)
	v_pk_mul_f32 v[174:175], v[174:175], v[198:199]
	v_pk_mul_f32 v[34:35], v[34:35], v[198:199]
	v_pk_fma_f32 v[172:173], v[172:173], v[196:197], v[174:175]
	v_pk_fma_f32 v[32:33], v[32:33], v[196:197], v[34:35]
	v_pk_mul_f32 v[34:35], v[164:165], v[196:197]
	v_pk_mul_f32 v[164:165], v[166:167], v[198:199]
	v_add_f32_e32 v166, v172, v173
	v_add_f32_e32 v32, v32, v33
	s_waitcnt lgkmcnt(6)
; #define LAS __attribute__((address_space(3)))
; __device__ __forceinline__ void rwkv_scan_prompt(const Params& p, LAS unsigned char* lds, int bh, int rq) {
;     ...
;             for (int tk = 0; tk < TC; ++tk) {
;                 f32x4 nr4 = r4, nd4 = d4, nk4 = k4, na4 = a4, nb4 = b4; float nvv = vv;
;                 if (tk < TC - 1) {
;                     const LAS float* o = ob + (tk + 1) * 6 * 64;
;                     nr4 = *(const LAS f32x4*)(o + cg_ * 4); nd4 = *(const LAS f32x4*)(o + 64 + cg_ * 4); nk4 = *(const LAS f32x4*)(o + 128 + cg_ * 4);
;                     na4 = *(const LAS f32x4*)(o + 256 + cg_ * 4); nb4 = *(const LAS f32x4*)(o + 320 + cg_ * 4);
;                     nvv = o[192 + rq * 16 + rloc];
;                 }
;                 __builtin_amdgcn_sched_barrier(0);
;                 typedef float f32x2_ __attribute__((ext_vector_type(2)));
;                 f32x2_ ta = (f32x2_){S[0], S[1]} * (f32x2_){a4[0], a4[1]}; ta = (f32x2_){S[2], S[3]} * (f32x2_){a4[2], a4[3]} + ta;
;                 f32x2_ ty = (f32x2_){S[0], S[1]} * (f32x2_){rp[0], rp[1]}; ty = (f32x2_){S[2], S[3]} * (f32x2_){rp[2], rp[3]} + ty;
;                 const f32x4 T = S * d4 + vv * k4;
;                 float sa = ta[0] + ta[1];
;                 float yp = ty[0] + ty[1];
;                 sa = dpp_add<0xB1>(sa); yp = dpp_add<0xB1>(yp);
;                 sa = dpp_add<0x4E>(sa); yp = dpp_add<0x4E>(yp);
;                 sa = dpp_add<0x124>(sa); yp = dpp_add<0x124>(yp);
;                 sa = dpp_add<0x128>(sa); yp = dpp_add<0x128>(yp);
;                 if (tk > 0) yk[(tk - 1) >> 4] = (cg_ == ((tk - 1) & 15)) ? yp : yk[(tk - 1) >> 4];
;                 S = sa * b4 + T;
;                 rp = r4;
;                 r4 = nr4; d4 = nd4; k4 = nk4; a4 = na4; b4 = nb4; vv = nvv;
	v_pk_fma_f32 v[164:165], v[170:171], v[202:203], v[164:165] op_sel_hi:[1,0,1]
	v_add_f32_dpp v33, v166, v166 quad_perm:[1,0,3,2] row_mask:0xf bank_mask:0xf bound_ctrl:1
	v_add_f32_dpp v32, v32, v32 quad_perm:[1,0,3,2] row_mask:0xf bank_mask:0xf bound_ctrl:1
	v_pk_fma_f32 v[34:35], v[168:169], v[202:203], v[34:35] op_sel_hi:[1,0,1]
	v_add_f32_dpp v33, v33, v33 quad_perm:[2,3,0,1] row_mask:0xf bank_mask:0xf bound_ctrl:1
	v_add_f32_dpp v32, v32, v32 quad_perm:[2,3,0,1] row_mask:0xf bank_mask:0xf bound_ctrl:1
	s_nop 0
	v_add_f32_dpp v33, v33, v33 row_ror:4 row_mask:0xf bank_mask:0xf bound_ctrl:1
	v_add_f32_dpp v166, v32, v32 row_ror:4 row_mask:0xf bank_mask:0xf bound_ctrl:1
	s_nop 0
	v_add_f32_dpp v32, v33, v33 row_ror:8 row_mask:0xf bank_mask:0xf bound_ctrl:1
	v_add_f32_dpp v33, v166, v166 row_ror:8 row_mask:0xf bank_mask:0xf bound_ctrl:1
	v_cndmask_b32_e64 v31, v31, v33, s[28:29]
	v_pk_fma_f32 v[196:197], v[176:177], v[32:33], v[34:35] op_sel_hi:[1,0,1]
	v_pk_fma_f32 v[198:199], v[178:179], v[32:33], v[164:165] op_sel_hi:[1,0,1]
	ds_read_b128 v[32:35], v28 offset:46080
	ds_read_b128 v[164:167], v28 offset:46336
	ds_read_b128 v[168:171], v28 offset:46592
	ds_read_b128 v[172:175], v28 offset:47104
	ds_read_b128 v[176:179], v28 offset:47360
	ds_read_b32 v202, v29 offset:46848
	s_waitcnt lgkmcnt(8)
	v_pk_mul_f32 v[190:191], v[190:191], v[198:199]
	v_pk_mul_f32 v[162:163], v[162:163], v[198:199]
	v_pk_fma_f32 v[188:189], v[188:189], v[196:197], v[190:191]
	v_pk_fma_f32 v[160:161], v[160:161], v[196:197], v[162:163]
	v_pk_mul_f32 v[162:163], v[180:181], v[196:197]
	v_pk_mul_f32 v[180:181], v[182:183], v[198:199]
	v_add_f32_e32 v182, v188, v189
	v_add_f32_e32 v160, v160, v161
	s_waitcnt lgkmcnt(6)
	v_pk_fma_f32 v[180:181], v[186:187], v[200:201], v[180:181] op_sel_hi:[1,0,1]
	v_add_f32_dpp v161, v182, v182 quad_perm:[1,0,3,2] row_mask:0xf bank_mask:0xf bound_ctrl:1
	v_add_f32_dpp v160, v160, v160 quad_perm:[1,0,3,2] row_mask:0xf bank_mask:0xf bound_ctrl:1
	v_pk_fma_f32 v[162:163], v[184:185], v[200:201], v[162:163] op_sel_hi:[1,0,1]
	v_add_f32_dpp v161, v161, v161 quad_perm:[2,3,0,1] row_mask:0xf bank_mask:0xf bound_ctrl:1
	v_add_f32_dpp v160, v160, v160 quad_perm:[2,3,0,1] row_mask:0xf bank_mask:0xf bound_ctrl:1
	s_nop 0
	v_add_f32_dpp v161, v161, v161 row_ror:4 row_mask:0xf bank_mask:0xf bound_ctrl:1
	v_add_f32_dpp v182, v160, v160 row_ror:4 row_mask:0xf bank_mask:0xf bound_ctrl:1
	s_nop 0
	v_add_f32_dpp v160, v161, v161 row_ror:8 row_mask:0xf bank_mask:0xf bound_ctrl:1
	v_add_f32_dpp v161, v182, v182 row_ror:8 row_mask:0xf bank_mask:0xf bound_ctrl:1
	v_cndmask_b32_e64 v31, v31, v161, s[30:31]
	v_pk_fma_f32 v[196:197], v[192:193], v[160:161], v[162:163] op_sel_hi:[1,0,1]
	v_pk_fma_f32 v[198:199], v[194:195], v[160:161], v[180:181] op_sel_hi:[1,0,1]
	ds_read_b128 v[160:163], v28 offset:47616
	ds_read_b128 v[180:183], v28 offset:47872
	ds_read_b128 v[184:187], v28 offset:48128
	ds_read_b128 v[188:191], v28 offset:48640
	ds_read_b128 v[192:195], v28 offset:48896
	ds_read_b32 v28, v29 offset:48384
	s_waitcnt lgkmcnt(8)
	v_pk_mul_f32 v[174:175], v[174:175], v[198:199]
	v_pk_mul_f32 v[26:27], v[26:27], v[198:199]
	v_pk_fma_f32 v[172:173], v[172:173], v[196:197], v[174:175]
	v_pk_fma_f32 v[24:25], v[24:25], v[196:197], v[26:27]
	v_add_f32_e32 v29, v172, v173
	v_add_f32_e32 v24, v24, v25
	v_pk_mul_f32 v[26:27], v[164:165], v[196:197]
	v_add_f32_dpp v25, v29, v29 quad_perm:[1,0,3,2] row_mask:0xf bank_mask:0xf bound_ctrl:1
	v_add_f32_dpp v24, v24, v24 quad_perm:[1,0,3,2] row_mask:0xf bank_mask:0xf bound_ctrl:1
	v_pk_mul_f32 v[164:165], v[166:167], v[198:199]
	v_add_f32_dpp v25, v25, v25 quad_perm:[2,3,0,1] row_mask:0xf bank_mask:0xf bound_ctrl:1
	v_add_f32_dpp v24, v24, v24 quad_perm:[2,3,0,1] row_mask:0xf bank_mask:0xf bound_ctrl:1
	s_waitcnt lgkmcnt(6)
; __device__ __forceinline__ float row_sum16(float x) { x = dpp_add<0xB1>(x); x = dpp_add<0x4E>(x); x = dpp_add<0x124>(x); x = dpp_add<0x128>(x); return x; }
; __device__ __forceinline__ void rwkv_scan_prompt(const Params& p, LAS unsigned char* lds, int bh, int rq) {
;     ...
;                 if (tk > 0) yk[(tk - 1) >> 4] = (cg_ == ((tk - 1) & 15)) ? yp : yk[(tk - 1) >> 4];
;                 S = sa * b4 + T;
;                 rp = r4;
;                 r4 = nr4; d4 = nd4; k4 = nk4; a4 = na4; b4 = nb4; vv = nvv;
;             }
;             {
;                 float yp = S[0] * rp[0] + S[1] * rp[1] + S[2] * rp[2] + S[3] * rp[3];
;                 yp = row_sum16(yp);
;                 yk[(TC - 1) >> 4] = (cg_ == ((TC - 1) & 15)) ? yp : yk[(TC - 1) >> 4];
;             }
; #pragma unroll
;             for (int j = 0; j < TC / 16; ++j) yk[j] += RKB[buf * TC + j * 16 + cg_] * ob[(j * 16 + cg_) * 6 * 64 + 192 + rq * 16 + rloc];
; #pragma unroll
;             for (int j = 0; j < TC / 16; ++j) YRAW[(size_t)(rowbase + c * TC + j * 16 + cg_) * 512 + h * 64 + rq * 16 + rloc] = yk[j];
	v_pk_fma_f32 v[164:165], v[170:171], v[202:203], v[164:165] op_sel_hi:[1,0,1]
	v_add_f32_dpp v25, v25, v25 row_ror:4 row_mask:0xf bank_mask:0xf bound_ctrl:1
	v_add_f32_dpp v29, v24, v24 row_ror:4 row_mask:0xf bank_mask:0xf bound_ctrl:1
	v_pk_fma_f32 v[26:27], v[168:169], v[202:203], v[26:27] op_sel_hi:[1,0,1]
	v_add_f32_dpp v24, v25, v25 row_ror:8 row_mask:0xf bank_mask:0xf bound_ctrl:1
	v_add_f32_dpp v25, v29, v29 row_ror:8 row_mask:0xf bank_mask:0xf bound_ctrl:1
	v_cndmask_b32_e64 v29, v31, v25, s[34:35]
	v_pk_fma_f32 v[26:27], v[176:177], v[24:25], v[26:27] op_sel_hi:[1,0,1]
	v_pk_fma_f32 v[24:25], v[178:179], v[24:25], v[164:165] op_sel_hi:[1,0,1]
	s_waitcnt lgkmcnt(2)
	v_pk_mul_f32 v[164:165], v[190:191], v[24:25]
	v_pk_mul_f32 v[34:35], v[34:35], v[24:25]
	v_pk_fma_f32 v[164:165], v[188:189], v[26:27], v[164:165]
	v_pk_fma_f32 v[32:33], v[32:33], v[26:27], v[34:35]
	v_pk_mul_f32 v[26:27], v[180:181], v[26:27]
	v_pk_mul_f32 v[24:25], v[182:183], v[24:25]
	s_waitcnt lgkmcnt(0)
	v_pk_fma_f32 v[34:35], v[184:185], v[28:29], v[26:27] op_sel_hi:[1,0,1]
	v_add_f32_e32 v26, v164, v165
	v_add_f32_e32 v27, v32, v33
	v_pk_fma_f32 v[24:25], v[186:187], v[28:29], v[24:25] op_sel_hi:[1,0,1]
	v_add_f32_dpp v26, v26, v26 quad_perm:[1,0,3,2] row_mask:0xf bank_mask:0xf bound_ctrl:1
	v_add_f32_dpp v27, v27, v27 quad_perm:[1,0,3,2] row_mask:0xf bank_mask:0xf bound_ctrl:1
	s_lshl_b32 s79, s94, 2
	v_add_f32_dpp v26, v26, v26 quad_perm:[2,3,0,1] row_mask:0xf bank_mask:0xf bound_ctrl:1
	v_add_f32_dpp v27, v27, v27 quad_perm:[2,3,0,1] row_mask:0xf bank_mask:0xf bound_ctrl:1
	s_add_i32 s79, s79, s78
	v_add_f32_dpp v26, v26, v26 row_ror:4 row_mask:0xf bank_mask:0xf bound_ctrl:1
	v_add_f32_dpp v27, v27, v27 row_ror:4 row_mask:0xf bank_mask:0xf bound_ctrl:1
	v_add3_u32 v32, s79, v135, v84
	v_add_f32_dpp v28, v26, v26 row_ror:8 row_mask:0xf bank_mask:0xf bound_ctrl:1
	v_add_f32_dpp v26, v27, v27 row_ror:8 row_mask:0xf bank_mask:0xf bound_ctrl:1
	v_cndmask_b32_e64 v31, v29, v26, s[36:37]
	v_pk_fma_f32 v[26:27], v[194:195], v[28:29], v[24:25] op_sel_hi:[1,0,1]
	v_pk_fma_f32 v[24:25], v[192:193], v[28:29], v[34:35] op_sel_hi:[1,0,1]
	ds_read2st64_b32 v[32:33], v32 offset0:3 offset1:99
	v_mul_f32_e32 v28, v161, v25
	v_fmac_f32_e32 v28, v160, v24
	v_fmac_f32_e32 v28, v162, v26
	v_fmac_f32_e32 v28, v163, v27
	s_nop 1
	v_add_f32_dpp v34, v28, v28 quad_perm:[1,0,3,2] row_mask:0xf bank_mask:0xf bound_ctrl:1
	v_lshl_add_u32 v28, s95, 7, v126
	ds_read2_b32 v[28:29], v28 offset1:16
	v_add_f32_dpp v34, v34, v34 quad_perm:[2,3,0,1] row_mask:0xf bank_mask:0xf bound_ctrl:1
	s_waitcnt lgkmcnt(0)
	v_fmac_f32_e32 v30, v28, v32
	v_add_f32_dpp v34, v34, v34 row_ror:4 row_mask:0xf bank_mask:0xf bound_ctrl:1
	v_add_u32_e32 v28, s0, v159
	s_nop 0
	v_add_f32_dpp v34, v34, v34 row_ror:8 row_mask:0xf bank_mask:0xf bound_ctrl:1
	v_cndmask_b32_e64 v31, v31, v34, s[4:5]
	v_fmac_f32_e32 v31, v29, v33
	v_ashrrev_i32_e32 v29, 31, v28
	v_lshlrev_b64 v[32:33], 11, v[28:29]
	v_add_u32_e32 v28, 16, v28
	v_ashrrev_i32_e32 v29, 31, v28
	v_lshlrev_b64 v[28:29], 11, v[28:29]
	v_lshl_add_u64 v[32:33], v[88:89], 0, v[32:33]
	v_lshl_add_u64 v[28:29], v[88:89], 0, v[28:29]
	global_store_dword v[32:33], v30, off sc0 sc1
	global_store_dword v[28:29], v31, off sc0 sc1
